# MF=3 GEMM loops (cin, qkv, resid) restructured to 8 barriers per K iteration: phase pairs merged, DMA schedule 2/6/2/6 with uniform vmcnt(8), first-iteration SrcC=0 peel kept
# baseline (speedup 1.0000x reference)
.LBB0_383:
	s_ashr_i32 s49, s48, 31
	s_lshl_b64 s[52:53], s[48:49], 19
	s_add_u32 s52, s10, s52
	s_addc_u32 s53, s11, s53
	s_and_b64 s[42:43], s[42:43], exec
	s_cselect_b32 s49, s53, s55
	s_cselect_b32 s66, s52, s54
	s_add_u32 s42, s56, 0x30080
	s_addc_u32 s43, s57, 0
	s_add_u32 s67, s54, 0x100
	s_addc_u32 s68, s55, 0
	s_mov_b32 s69, -2
	s_add_u32 s54, s42, 0xfffd0080
	s_addc_u32 s55, s43, -1
	s_add_i32 s70, 0, 0x10000
	v_add_u32_e32 v96, s70, v157
	ds_read_b128 v[160:163], v96
	ds_read_b128 v[164:167], v96 offset:1024
	ds_read_b128 v[168:171], v96 offset:2048
	ds_read_b128 v[172:175], v96 offset:3072
	s_cmp_eq_u32 s69, 12
	s_cselect_b32 s57, s51, s55
	s_cselect_b32 s56, s50, s54
	s_cselect_b32 s55, s49, s68
	s_cselect_b32 s54, s66, s67
	s_add_i32 m0, s28, 0xc000
	ds_read_b128 v[182:185], v159
	ds_read_b128 v[186:189], v159 offset:1024
	ds_read_b128 v[190:193], v159 offset:2048
	ds_read_b128 v[194:197], v159 offset:3072
	ds_read_b128 v[198:201], v159 offset:4096
	ds_read_b128 v[224:227], v159 offset:5120
	global_load_lds_dwordx4 v150, s[42:43]
	s_add_i32 m0, s28, 0xe000
	s_mov_b64 exec, s[98:99]
	global_load_lds_dwordx4 v152, s[42:43]
	s_mov_b64 exec, -1
	s_add_i32 s72, 0, 0x14000
	s_add_i32 s70, s70, s18
	v_add_u32_e32 v96, s72, v157
	v_lshl_add_u64 v[154:155], s[54:55], 0, v[142:143]
	ds_read_b128 v[228:231], v96
	ds_read_b128 v[232:235], v96 offset:1024
	ds_read_b128 v[236:239], v96 offset:2048
	ds_read_b128 v[240:243], v96 offset:3072
	v_lshl_add_u64 v[176:177], s[54:55], 0, v[138:139]
	s_waitcnt vmcnt(8)
	s_waitcnt lgkmcnt(4)
	s_setprio 1
	s_barrier
	s_waitcnt lgkmcnt(0)
	v_mfma_f32_16x16x32_bf16 v[134:137], v[160:163], v[182:185], 0
	v_mfma_f32_16x16x32_bf16 v[130:133], v[168:171], v[182:185], 0
	v_mfma_f32_16x16x32_bf16 v[118:121], v[160:163], v[190:193], 0
	v_mfma_f32_16x16x32_bf16 v[114:117], v[168:171], v[190:193], 0
	v_mfma_f32_16x16x32_bf16 v[102:105], v[160:163], v[198:201], 0
	v_mfma_f32_16x16x32_bf16 v[98:101], v[168:171], v[198:201], 0
	v_mfma_f32_16x16x32_bf16 v[134:137], v[164:167], v[186:189], v[134:137]
	v_mfma_f32_16x16x32_bf16 v[130:133], v[172:175], v[186:189], v[130:133]
	v_mfma_f32_16x16x32_bf16 v[118:121], v[164:167], v[194:197], v[118:121]
	v_mfma_f32_16x16x32_bf16 v[114:117], v[172:175], v[194:197], v[114:117]
	v_mfma_f32_16x16x32_bf16 v[102:105], v[164:167], v[224:227], v[102:105]
	v_mfma_f32_16x16x32_bf16 v[98:101], v[172:175], v[224:227], v[98:101]
	v_mfma_f32_16x16x32_bf16 v[126:129], v[228:231], v[182:185], 0
	v_mfma_f32_16x16x32_bf16 v[122:125], v[236:239], v[182:185], 0
	v_mfma_f32_16x16x32_bf16 v[110:113], v[228:231], v[190:193], 0
	s_mov_b32 m0, s28
	v_mfma_f32_16x16x32_bf16 v[106:109], v[236:239], v[190:193], 0
	v_lshl_add_u64 v[202:203], s[56:57], 0, v[144:145]
	v_mfma_f32_16x16x32_bf16 v[92:95], v[228:231], v[198:201], 0
	v_mfma_f32_16x16x32_bf16 v[88:91], v[236:239], v[198:201], 0
	v_mfma_f32_16x16x32_bf16 v[126:129], v[232:235], v[186:189], v[126:129]
	v_mfma_f32_16x16x32_bf16 v[122:125], v[240:243], v[186:189], v[122:125]
	v_mfma_f32_16x16x32_bf16 v[110:113], v[232:235], v[194:197], v[110:113]
	v_mfma_f32_16x16x32_bf16 v[106:109], v[240:243], v[194:197], v[106:109]
	v_mfma_f32_16x16x32_bf16 v[92:95], v[232:235], v[224:227], v[92:95]
	v_mfma_f32_16x16x32_bf16 v[88:91], v[240:243], v[224:227], v[88:91]
	s_barrier
	s_setprio 0
	s_mov_b32 m0, s70
	s_nop 0
	global_load_lds_dwordx4 v142, s[54:55]
	s_add_i32 m0, s70, 0x2000
	s_nop 0
	global_load_lds_dwordx4 v138, s[54:55]
	s_mov_b32 m0, s28
	ds_read_b128 v[182:185], v159 offset:16384
	ds_read_b128 v[186:189], v159 offset:17408
	ds_read_b128 v[190:193], v159 offset:18432
	ds_read_b128 v[194:197], v159 offset:19456
	ds_read_b128 v[198:201], v159 offset:20480
	ds_read_b128 v[224:227], v159 offset:21504
	global_load_lds_dwordx4 v144, s[56:57]
	v_lshl_add_u64 v[244:245], s[56:57], 0, v[140:141]
	s_mov_b32 m0, s37
	s_mov_b64 exec, s[98:99]
	global_load_lds_dwordx4 v140, s[56:57]
	s_mov_b64 exec, -1
	s_add_u32 s70, s54, 0x40000
	s_addc_u32 s71, s55, 0
	s_add_i32 s72, s72, s18
	s_mov_b32 m0, s72
	s_nop 0
	global_load_lds_dwordx4 v142, s[70:71]
	s_add_i32 m0, s72, 0x2000
	s_nop 0
	global_load_lds_dwordx4 v138, s[70:71]
	s_waitcnt vmcnt(8)
	s_waitcnt lgkmcnt(0)
	s_setprio 1
	s_barrier
	v_mfma_f32_16x16x32_bf16 v[84:87], v[160:163], v[182:185], 0
	v_mfma_f32_16x16x32_bf16 v[80:83], v[168:171], v[182:185], 0
	v_mfma_f32_16x16x32_bf16 v[68:71], v[160:163], v[190:193], 0
	v_mfma_f32_16x16x32_bf16 v[64:67], v[168:171], v[190:193], 0
	v_mfma_f32_16x16x32_bf16 v[28:31], v[160:163], v[198:201], 0
	v_mfma_f32_16x16x32_bf16 v[24:27], v[168:171], v[198:201], 0
	v_mfma_f32_16x16x32_bf16 v[84:87], v[164:167], v[186:189], v[84:87]
	v_mfma_f32_16x16x32_bf16 v[80:83], v[172:175], v[186:189], v[80:83]
	v_mfma_f32_16x16x32_bf16 v[68:71], v[164:167], v[194:197], v[68:71]
	v_mfma_f32_16x16x32_bf16 v[64:67], v[172:175], v[194:197], v[64:67]
	v_mfma_f32_16x16x32_bf16 v[28:31], v[164:167], v[224:227], v[28:31]
	v_mfma_f32_16x16x32_bf16 v[24:27], v[172:175], v[224:227], v[24:27]
	v_mfma_f32_16x16x32_bf16 v[76:79], v[228:231], v[182:185], 0
	v_mfma_f32_16x16x32_bf16 v[72:75], v[236:239], v[182:185], 0
	v_mfma_f32_16x16x32_bf16 v[60:63], v[228:231], v[190:193], 0
	s_add_i32 s70, 0, 0x18000
	v_mfma_f32_16x16x32_bf16 v[56:59], v[236:239], v[190:193], 0
	v_add_u32_e32 v96, s70, v157
	v_mfma_f32_16x16x32_bf16 v[20:23], v[228:231], v[198:201], 0
	v_mfma_f32_16x16x32_bf16 v[16:19], v[236:239], v[198:201], 0
	v_mfma_f32_16x16x32_bf16 v[76:79], v[232:235], v[186:189], v[76:79]
	v_mfma_f32_16x16x32_bf16 v[72:75], v[240:243], v[186:189], v[72:75]
	v_mfma_f32_16x16x32_bf16 v[60:63], v[232:235], v[194:197], v[60:63]
	v_mfma_f32_16x16x32_bf16 v[56:59], v[240:243], v[194:197], v[56:59]
	v_mfma_f32_16x16x32_bf16 v[20:23], v[232:235], v[224:227], v[20:23]
	v_mfma_f32_16x16x32_bf16 v[16:19], v[240:243], v[224:227], v[16:19]
	s_barrier
	s_setprio 0
	ds_read_b128 v[160:163], v96
	ds_read_b128 v[164:167], v96 offset:1024
	ds_read_b128 v[168:171], v96 offset:2048
	ds_read_b128 v[172:175], v96 offset:3072
	s_add_u32 s56, s56, 0x30000
	s_addc_u32 s57, s57, 0
	s_mov_b32 m0, s58
	ds_read_b128 v[182:185], v159 offset:32768
	ds_read_b128 v[186:189], v159 offset:33792
	ds_read_b128 v[190:193], v159 offset:34816
	ds_read_b128 v[194:197], v159 offset:35840
	ds_read_b128 v[198:201], v159 offset:36864
	ds_read_b128 v[224:227], v159 offset:37888
	global_load_lds_dwordx4 v144, s[56:57]
	s_mov_b32 m0, s59
	s_mov_b64 exec, s[98:99]
	global_load_lds_dwordx4 v140, s[56:57]
	s_mov_b64 exec, -1
	s_add_i32 s56, 0, 0x1c000
	s_add_i32 s57, s70, s18
	v_add_u32_e32 v96, s56, v157
	ds_read_b128 v[228:231], v96
	ds_read_b128 v[232:235], v96 offset:1024
	ds_read_b128 v[236:239], v96 offset:2048
	ds_read_b128 v[240:243], v96 offset:3072
	s_waitcnt vmcnt(8)
	s_waitcnt lgkmcnt(4)
	s_setprio 1
	s_barrier
	s_waitcnt lgkmcnt(0)
	v_mfma_f32_16x16x32_bf16 v[134:137], v[160:163], v[182:185], v[134:137]
	v_mfma_f32_16x16x32_bf16 v[130:133], v[168:171], v[182:185], v[130:133]
	v_mfma_f32_16x16x32_bf16 v[118:121], v[160:163], v[190:193], v[118:121]
	v_mfma_f32_16x16x32_bf16 v[114:117], v[168:171], v[190:193], v[114:117]
	v_mfma_f32_16x16x32_bf16 v[102:105], v[160:163], v[198:201], v[102:105]
	v_mfma_f32_16x16x32_bf16 v[98:101], v[168:171], v[198:201], v[98:101]
	v_mfma_f32_16x16x32_bf16 v[134:137], v[164:167], v[186:189], v[134:137]
	v_mfma_f32_16x16x32_bf16 v[130:133], v[172:175], v[186:189], v[130:133]
	v_mfma_f32_16x16x32_bf16 v[118:121], v[164:167], v[194:197], v[118:121]
	v_mfma_f32_16x16x32_bf16 v[114:117], v[172:175], v[194:197], v[114:117]
	v_mfma_f32_16x16x32_bf16 v[102:105], v[164:167], v[224:227], v[102:105]
	v_mfma_f32_16x16x32_bf16 v[98:101], v[172:175], v[224:227], v[98:101]
	v_mfma_f32_16x16x32_bf16 v[126:129], v[228:231], v[182:185], v[126:129]
	v_mfma_f32_16x16x32_bf16 v[122:125], v[236:239], v[182:185], v[122:125]
	v_mfma_f32_16x16x32_bf16 v[110:113], v[228:231], v[190:193], v[110:113]
	s_mov_b32 m0, s60
	v_mfma_f32_16x16x32_bf16 v[106:109], v[236:239], v[190:193], v[106:109]
	v_lshl_add_u64 v[154:155], v[202:203], 0, s[6:7]
	v_mfma_f32_16x16x32_bf16 v[92:95], v[228:231], v[198:201], v[92:95]
	v_mfma_f32_16x16x32_bf16 v[88:91], v[236:239], v[198:201], v[88:91]
	v_mfma_f32_16x16x32_bf16 v[126:129], v[232:235], v[186:189], v[126:129]
	v_mfma_f32_16x16x32_bf16 v[122:125], v[240:243], v[186:189], v[122:125]
	v_mfma_f32_16x16x32_bf16 v[110:113], v[232:235], v[194:197], v[110:113]
	v_mfma_f32_16x16x32_bf16 v[106:109], v[240:243], v[194:197], v[106:109]
	v_mfma_f32_16x16x32_bf16 v[92:95], v[232:235], v[224:227], v[92:95]
	v_mfma_f32_16x16x32_bf16 v[88:91], v[240:243], v[224:227], v[88:91]
	s_barrier
	s_setprio 0
	v_lshl_add_u64 v[154:155], s[54:55], 0, v[142:143]
	v_lshl_add_u64 v[154:155], v[154:155], 0, s[6:7]
	s_mov_b32 m0, s57
	s_nop 0
	global_load_lds_dwordx4 v[154:155], off
	v_lshl_add_u64 v[154:155], v[176:177], 0, s[6:7]
	s_add_i32 m0, s57, 0x2000
	s_nop 0
	global_load_lds_dwordx4 v[154:155], off
	s_mov_b32 m0, s60
	v_lshl_add_u64 v[154:155], v[202:203], 0, s[6:7]
	ds_read_b128 v[182:185], v159 offset:49152
	ds_read_b128 v[186:189], v159 offset:50176
	ds_read_b128 v[190:193], v159 offset:51200
	ds_read_b128 v[194:197], v159 offset:52224
	ds_read_b128 v[198:201], v159 offset:53248
	ds_read_b128 v[224:227], v159 offset:54272
	global_load_lds_dwordx4 v[154:155], off
	v_lshl_add_u64 v[154:155], v[244:245], 0, s[6:7]
	s_mov_b32 m0, s61
	s_mov_b64 exec, s[98:99]
	global_load_lds_dwordx4 v[154:155], off
	s_mov_b64 exec, -1
	s_add_u32 s54, s54, 0x40080
	s_addc_u32 s55, s55, 0
	s_add_i32 s56, s56, s18
	s_mov_b32 m0, s56
	s_nop 0
	global_load_lds_dwordx4 v142, s[54:55]
	s_add_i32 m0, s56, 0x2000
	s_nop 0
	global_load_lds_dwordx4 v138, s[54:55]
	s_waitcnt vmcnt(8)
	s_waitcnt lgkmcnt(0)
	s_setprio 1
	s_barrier
	v_mfma_f32_16x16x32_bf16 v[84:87], v[160:163], v[182:185], v[84:87]
	v_mfma_f32_16x16x32_bf16 v[80:83], v[168:171], v[182:185], v[80:83]
	v_mfma_f32_16x16x32_bf16 v[68:71], v[160:163], v[190:193], v[68:71]
	v_mfma_f32_16x16x32_bf16 v[64:67], v[168:171], v[190:193], v[64:67]
	v_mfma_f32_16x16x32_bf16 v[28:31], v[160:163], v[198:201], v[28:31]
	v_mfma_f32_16x16x32_bf16 v[24:27], v[168:171], v[198:201], v[24:27]
	v_mfma_f32_16x16x32_bf16 v[84:87], v[164:167], v[186:189], v[84:87]
	v_mfma_f32_16x16x32_bf16 v[80:83], v[172:175], v[186:189], v[80:83]
	v_mfma_f32_16x16x32_bf16 v[68:71], v[164:167], v[194:197], v[68:71]
	v_mfma_f32_16x16x32_bf16 v[64:67], v[172:175], v[194:197], v[64:67]
	v_mfma_f32_16x16x32_bf16 v[28:31], v[164:167], v[224:227], v[28:31]
	v_mfma_f32_16x16x32_bf16 v[24:27], v[172:175], v[224:227], v[24:27]
	v_mfma_f32_16x16x32_bf16 v[76:79], v[228:231], v[182:185], v[76:79]
	v_mfma_f32_16x16x32_bf16 v[72:75], v[236:239], v[182:185], v[72:75]
	v_mfma_f32_16x16x32_bf16 v[60:63], v[228:231], v[190:193], v[60:63]
	s_add_i32 s69, s69, 2
	v_mfma_f32_16x16x32_bf16 v[56:59], v[236:239], v[190:193], v[56:59]
	s_add_u32 s42, s42, 0x100
	v_mfma_f32_16x16x32_bf16 v[20:23], v[228:231], v[198:201], v[20:23]
	s_addc_u32 s43, s43, 0
	v_mfma_f32_16x16x32_bf16 v[16:19], v[236:239], v[198:201], v[16:19]
	s_add_u32 s67, s67, 0x100
	v_mfma_f32_16x16x32_bf16 v[76:79], v[232:235], v[186:189], v[76:79]
	s_addc_u32 s68, s68, 0
	v_mfma_f32_16x16x32_bf16 v[72:75], v[240:243], v[186:189], v[72:75]
	s_cmp_gt_u32 s69, 13
	v_mfma_f32_16x16x32_bf16 v[60:63], v[232:235], v[194:197], v[60:63]
	v_mfma_f32_16x16x32_bf16 v[56:59], v[240:243], v[194:197], v[56:59]
	v_mfma_f32_16x16x32_bf16 v[20:23], v[232:235], v[224:227], v[20:23]
	v_mfma_f32_16x16x32_bf16 v[16:19], v[240:243], v[224:227], v[16:19]
	s_barrier
	s_setprio 0
.LBB0_384:
	s_add_u32 s54, s42, 0xfffd0080
	s_addc_u32 s55, s43, -1
	s_add_i32 s70, 0, 0x10000
	v_add_u32_e32 v96, s70, v157
	ds_read_b128 v[160:163], v96
	ds_read_b128 v[164:167], v96 offset:1024
	ds_read_b128 v[168:171], v96 offset:2048
	ds_read_b128 v[172:175], v96 offset:3072
	s_cmp_eq_u32 s69, 12
	s_cselect_b32 s57, s51, s55
	s_cselect_b32 s56, s50, s54
	s_cselect_b32 s55, s49, s68
	s_cselect_b32 s54, s66, s67
	s_add_i32 m0, s28, 0xc000
	ds_read_b128 v[182:185], v159
	ds_read_b128 v[186:189], v159 offset:1024
	ds_read_b128 v[190:193], v159 offset:2048
	ds_read_b128 v[194:197], v159 offset:3072
	ds_read_b128 v[198:201], v159 offset:4096
	ds_read_b128 v[224:227], v159 offset:5120
	global_load_lds_dwordx4 v150, s[42:43]
	s_add_i32 m0, s28, 0xe000
	s_mov_b64 exec, s[98:99]
	global_load_lds_dwordx4 v152, s[42:43]
	s_mov_b64 exec, -1
	s_add_i32 s72, 0, 0x14000
	s_add_i32 s70, s70, s18
	v_add_u32_e32 v96, s72, v157
	v_lshl_add_u64 v[154:155], s[54:55], 0, v[142:143]
	ds_read_b128 v[228:231], v96
	ds_read_b128 v[232:235], v96 offset:1024
	ds_read_b128 v[236:239], v96 offset:2048
	ds_read_b128 v[240:243], v96 offset:3072
	v_lshl_add_u64 v[176:177], s[54:55], 0, v[138:139]
	s_waitcnt vmcnt(8)
	s_waitcnt lgkmcnt(4)
	s_setprio 1
	s_barrier
	s_waitcnt lgkmcnt(0)
	v_mfma_f32_16x16x32_bf16 v[134:137], v[160:163], v[182:185], v[134:137]
	v_mfma_f32_16x16x32_bf16 v[130:133], v[168:171], v[182:185], v[130:133]
	v_mfma_f32_16x16x32_bf16 v[118:121], v[160:163], v[190:193], v[118:121]
	v_mfma_f32_16x16x32_bf16 v[114:117], v[168:171], v[190:193], v[114:117]
	v_mfma_f32_16x16x32_bf16 v[102:105], v[160:163], v[198:201], v[102:105]
	v_mfma_f32_16x16x32_bf16 v[98:101], v[168:171], v[198:201], v[98:101]
	v_mfma_f32_16x16x32_bf16 v[134:137], v[164:167], v[186:189], v[134:137]
	v_mfma_f32_16x16x32_bf16 v[130:133], v[172:175], v[186:189], v[130:133]
	v_mfma_f32_16x16x32_bf16 v[118:121], v[164:167], v[194:197], v[118:121]
	v_mfma_f32_16x16x32_bf16 v[114:117], v[172:175], v[194:197], v[114:117]
	v_mfma_f32_16x16x32_bf16 v[102:105], v[164:167], v[224:227], v[102:105]
	v_mfma_f32_16x16x32_bf16 v[98:101], v[172:175], v[224:227], v[98:101]
	v_mfma_f32_16x16x32_bf16 v[126:129], v[228:231], v[182:185], v[126:129]
	v_mfma_f32_16x16x32_bf16 v[122:125], v[236:239], v[182:185], v[122:125]
	v_mfma_f32_16x16x32_bf16 v[110:113], v[228:231], v[190:193], v[110:113]
	s_mov_b32 m0, s28
	v_mfma_f32_16x16x32_bf16 v[106:109], v[236:239], v[190:193], v[106:109]
	v_lshl_add_u64 v[202:203], s[56:57], 0, v[144:145]
	v_mfma_f32_16x16x32_bf16 v[92:95], v[228:231], v[198:201], v[92:95]
	v_mfma_f32_16x16x32_bf16 v[88:91], v[236:239], v[198:201], v[88:91]
	v_mfma_f32_16x16x32_bf16 v[126:129], v[232:235], v[186:189], v[126:129]
	v_mfma_f32_16x16x32_bf16 v[122:125], v[240:243], v[186:189], v[122:125]
	v_mfma_f32_16x16x32_bf16 v[110:113], v[232:235], v[194:197], v[110:113]
	v_mfma_f32_16x16x32_bf16 v[106:109], v[240:243], v[194:197], v[106:109]
	v_mfma_f32_16x16x32_bf16 v[92:95], v[232:235], v[224:227], v[92:95]
	v_mfma_f32_16x16x32_bf16 v[88:91], v[240:243], v[224:227], v[88:91]
	s_barrier
	s_setprio 0
	s_mov_b32 m0, s70
	s_nop 0
	global_load_lds_dwordx4 v142, s[54:55]
	s_add_i32 m0, s70, 0x2000
	s_nop 0
	global_load_lds_dwordx4 v138, s[54:55]
	s_mov_b32 m0, s28
	ds_read_b128 v[182:185], v159 offset:16384
	ds_read_b128 v[186:189], v159 offset:17408
	ds_read_b128 v[190:193], v159 offset:18432
	ds_read_b128 v[194:197], v159 offset:19456
	ds_read_b128 v[198:201], v159 offset:20480
	ds_read_b128 v[224:227], v159 offset:21504
	global_load_lds_dwordx4 v144, s[56:57]
	v_lshl_add_u64 v[244:245], s[56:57], 0, v[140:141]
	s_mov_b32 m0, s37
	s_mov_b64 exec, s[98:99]
	global_load_lds_dwordx4 v140, s[56:57]
	s_mov_b64 exec, -1
	s_add_u32 s70, s54, 0x40000
	s_addc_u32 s71, s55, 0
	s_add_i32 s72, s72, s18
	s_mov_b32 m0, s72
	s_nop 0
	global_load_lds_dwordx4 v142, s[70:71]
	s_add_i32 m0, s72, 0x2000
	s_nop 0
	global_load_lds_dwordx4 v138, s[70:71]
	s_waitcnt vmcnt(8)
	s_waitcnt lgkmcnt(0)
	s_setprio 1
	s_barrier
	v_mfma_f32_16x16x32_bf16 v[84:87], v[160:163], v[182:185], v[84:87]
	v_mfma_f32_16x16x32_bf16 v[80:83], v[168:171], v[182:185], v[80:83]
	v_mfma_f32_16x16x32_bf16 v[68:71], v[160:163], v[190:193], v[68:71]
	v_mfma_f32_16x16x32_bf16 v[64:67], v[168:171], v[190:193], v[64:67]
	v_mfma_f32_16x16x32_bf16 v[28:31], v[160:163], v[198:201], v[28:31]
	v_mfma_f32_16x16x32_bf16 v[24:27], v[168:171], v[198:201], v[24:27]
	v_mfma_f32_16x16x32_bf16 v[84:87], v[164:167], v[186:189], v[84:87]
	v_mfma_f32_16x16x32_bf16 v[80:83], v[172:175], v[186:189], v[80:83]
	v_mfma_f32_16x16x32_bf16 v[68:71], v[164:167], v[194:197], v[68:71]
	v_mfma_f32_16x16x32_bf16 v[64:67], v[172:175], v[194:197], v[64:67]
	v_mfma_f32_16x16x32_bf16 v[28:31], v[164:167], v[224:227], v[28:31]
	v_mfma_f32_16x16x32_bf16 v[24:27], v[172:175], v[224:227], v[24:27]
	v_mfma_f32_16x16x32_bf16 v[76:79], v[228:231], v[182:185], v[76:79]
	v_mfma_f32_16x16x32_bf16 v[72:75], v[236:239], v[182:185], v[72:75]
	v_mfma_f32_16x16x32_bf16 v[60:63], v[228:231], v[190:193], v[60:63]
	s_add_i32 s70, 0, 0x18000
	v_mfma_f32_16x16x32_bf16 v[56:59], v[236:239], v[190:193], v[56:59]
	v_add_u32_e32 v96, s70, v157
	v_mfma_f32_16x16x32_bf16 v[20:23], v[228:231], v[198:201], v[20:23]
	v_mfma_f32_16x16x32_bf16 v[16:19], v[236:239], v[198:201], v[16:19]
	v_mfma_f32_16x16x32_bf16 v[76:79], v[232:235], v[186:189], v[76:79]
	v_mfma_f32_16x16x32_bf16 v[72:75], v[240:243], v[186:189], v[72:75]
	v_mfma_f32_16x16x32_bf16 v[60:63], v[232:235], v[194:197], v[60:63]
	v_mfma_f32_16x16x32_bf16 v[56:59], v[240:243], v[194:197], v[56:59]
	v_mfma_f32_16x16x32_bf16 v[20:23], v[232:235], v[224:227], v[20:23]
	v_mfma_f32_16x16x32_bf16 v[16:19], v[240:243], v[224:227], v[16:19]
	s_barrier
	s_setprio 0
	ds_read_b128 v[160:163], v96
	ds_read_b128 v[164:167], v96 offset:1024
	ds_read_b128 v[168:171], v96 offset:2048
	ds_read_b128 v[172:175], v96 offset:3072
	s_add_u32 s56, s56, 0x30000
	s_addc_u32 s57, s57, 0
	s_mov_b32 m0, s58
	ds_read_b128 v[182:185], v159 offset:32768
	ds_read_b128 v[186:189], v159 offset:33792
	ds_read_b128 v[190:193], v159 offset:34816
	ds_read_b128 v[194:197], v159 offset:35840
	ds_read_b128 v[198:201], v159 offset:36864
	ds_read_b128 v[224:227], v159 offset:37888
	global_load_lds_dwordx4 v144, s[56:57]
	s_mov_b32 m0, s59
	s_mov_b64 exec, s[98:99]
	global_load_lds_dwordx4 v140, s[56:57]
	s_mov_b64 exec, -1
	s_add_i32 s56, 0, 0x1c000
	s_add_i32 s57, s70, s18
	v_add_u32_e32 v96, s56, v157
	ds_read_b128 v[228:231], v96
	ds_read_b128 v[232:235], v96 offset:1024
	ds_read_b128 v[236:239], v96 offset:2048
	ds_read_b128 v[240:243], v96 offset:3072
	s_waitcnt vmcnt(8)
	s_waitcnt lgkmcnt(4)
	s_setprio 1
	s_barrier
	s_waitcnt lgkmcnt(0)
	v_mfma_f32_16x16x32_bf16 v[134:137], v[160:163], v[182:185], v[134:137]
	v_mfma_f32_16x16x32_bf16 v[130:133], v[168:171], v[182:185], v[130:133]
	v_mfma_f32_16x16x32_bf16 v[118:121], v[160:163], v[190:193], v[118:121]
	v_mfma_f32_16x16x32_bf16 v[114:117], v[168:171], v[190:193], v[114:117]
	v_mfma_f32_16x16x32_bf16 v[102:105], v[160:163], v[198:201], v[102:105]
	v_mfma_f32_16x16x32_bf16 v[98:101], v[168:171], v[198:201], v[98:101]
	v_mfma_f32_16x16x32_bf16 v[134:137], v[164:167], v[186:189], v[134:137]
	v_mfma_f32_16x16x32_bf16 v[130:133], v[172:175], v[186:189], v[130:133]
	v_mfma_f32_16x16x32_bf16 v[118:121], v[164:167], v[194:197], v[118:121]
	v_mfma_f32_16x16x32_bf16 v[114:117], v[172:175], v[194:197], v[114:117]
	v_mfma_f32_16x16x32_bf16 v[102:105], v[164:167], v[224:227], v[102:105]
	v_mfma_f32_16x16x32_bf16 v[98:101], v[172:175], v[224:227], v[98:101]
	v_mfma_f32_16x16x32_bf16 v[126:129], v[228:231], v[182:185], v[126:129]
	v_mfma_f32_16x16x32_bf16 v[122:125], v[236:239], v[182:185], v[122:125]
	v_mfma_f32_16x16x32_bf16 v[110:113], v[228:231], v[190:193], v[110:113]
	s_mov_b32 m0, s60
	v_mfma_f32_16x16x32_bf16 v[106:109], v[236:239], v[190:193], v[106:109]
	v_lshl_add_u64 v[154:155], v[202:203], 0, s[6:7]
	v_mfma_f32_16x16x32_bf16 v[92:95], v[228:231], v[198:201], v[92:95]
	v_mfma_f32_16x16x32_bf16 v[88:91], v[236:239], v[198:201], v[88:91]
	v_mfma_f32_16x16x32_bf16 v[126:129], v[232:235], v[186:189], v[126:129]
	v_mfma_f32_16x16x32_bf16 v[122:125], v[240:243], v[186:189], v[122:125]
	v_mfma_f32_16x16x32_bf16 v[110:113], v[232:235], v[194:197], v[110:113]
	v_mfma_f32_16x16x32_bf16 v[106:109], v[240:243], v[194:197], v[106:109]
	v_mfma_f32_16x16x32_bf16 v[92:95], v[232:235], v[224:227], v[92:95]
	v_mfma_f32_16x16x32_bf16 v[88:91], v[240:243], v[224:227], v[88:91]
	s_barrier
	s_setprio 0
	v_lshl_add_u64 v[154:155], s[54:55], 0, v[142:143]
	v_lshl_add_u64 v[154:155], v[154:155], 0, s[6:7]
	s_mov_b32 m0, s57
	s_nop 0
	global_load_lds_dwordx4 v[154:155], off
	v_lshl_add_u64 v[154:155], v[176:177], 0, s[6:7]
	s_add_i32 m0, s57, 0x2000
	s_nop 0
	global_load_lds_dwordx4 v[154:155], off
	s_mov_b32 m0, s60
	v_lshl_add_u64 v[154:155], v[202:203], 0, s[6:7]
	ds_read_b128 v[182:185], v159 offset:49152
	ds_read_b128 v[186:189], v159 offset:50176
	ds_read_b128 v[190:193], v159 offset:51200
	ds_read_b128 v[194:197], v159 offset:52224
	ds_read_b128 v[198:201], v159 offset:53248
	ds_read_b128 v[224:227], v159 offset:54272
	global_load_lds_dwordx4 v[154:155], off
	v_lshl_add_u64 v[154:155], v[244:245], 0, s[6:7]
	s_mov_b32 m0, s61
	s_mov_b64 exec, s[98:99]
	global_load_lds_dwordx4 v[154:155], off
	s_mov_b64 exec, -1
	s_add_u32 s54, s54, 0x40080
	s_addc_u32 s55, s55, 0
	s_add_i32 s56, s56, s18
	s_mov_b32 m0, s56
	s_nop 0
	global_load_lds_dwordx4 v142, s[54:55]
	s_add_i32 m0, s56, 0x2000
	s_nop 0
	global_load_lds_dwordx4 v138, s[54:55]
	s_waitcnt vmcnt(8)
	s_waitcnt lgkmcnt(0)
	s_setprio 1
	s_barrier
	v_mfma_f32_16x16x32_bf16 v[84:87], v[160:163], v[182:185], v[84:87]
	v_mfma_f32_16x16x32_bf16 v[80:83], v[168:171], v[182:185], v[80:83]
	v_mfma_f32_16x16x32_bf16 v[68:71], v[160:163], v[190:193], v[68:71]
	v_mfma_f32_16x16x32_bf16 v[64:67], v[168:171], v[190:193], v[64:67]
	v_mfma_f32_16x16x32_bf16 v[28:31], v[160:163], v[198:201], v[28:31]
	v_mfma_f32_16x16x32_bf16 v[24:27], v[168:171], v[198:201], v[24:27]
	v_mfma_f32_16x16x32_bf16 v[84:87], v[164:167], v[186:189], v[84:87]
	v_mfma_f32_16x16x32_bf16 v[80:83], v[172:175], v[186:189], v[80:83]
	v_mfma_f32_16x16x32_bf16 v[68:71], v[164:167], v[194:197], v[68:71]
	v_mfma_f32_16x16x32_bf16 v[64:67], v[172:175], v[194:197], v[64:67]
	v_mfma_f32_16x16x32_bf16 v[28:31], v[164:167], v[224:227], v[28:31]
	v_mfma_f32_16x16x32_bf16 v[24:27], v[172:175], v[224:227], v[24:27]
	v_mfma_f32_16x16x32_bf16 v[76:79], v[228:231], v[182:185], v[76:79]
	v_mfma_f32_16x16x32_bf16 v[72:75], v[236:239], v[182:185], v[72:75]
	v_mfma_f32_16x16x32_bf16 v[60:63], v[228:231], v[190:193], v[60:63]
	s_add_i32 s69, s69, 2
	v_mfma_f32_16x16x32_bf16 v[56:59], v[236:239], v[190:193], v[56:59]
	s_add_u32 s42, s42, 0x100
	v_mfma_f32_16x16x32_bf16 v[20:23], v[228:231], v[198:201], v[20:23]
	s_addc_u32 s43, s43, 0
	v_mfma_f32_16x16x32_bf16 v[16:19], v[236:239], v[198:201], v[16:19]
	s_add_u32 s67, s67, 0x100
	v_mfma_f32_16x16x32_bf16 v[76:79], v[232:235], v[186:189], v[76:79]
	s_addc_u32 s68, s68, 0
	v_mfma_f32_16x16x32_bf16 v[72:75], v[240:243], v[186:189], v[72:75]
	s_cmp_gt_u32 s69, 13
	v_mfma_f32_16x16x32_bf16 v[60:63], v[232:235], v[194:197], v[60:63]
	v_mfma_f32_16x16x32_bf16 v[56:59], v[240:243], v[194:197], v[56:59]
	v_mfma_f32_16x16x32_bf16 v[20:23], v[232:235], v[224:227], v[20:23]
	v_mfma_f32_16x16x32_bf16 v[16:19], v[240:243], v[224:227], v[16:19]
	s_barrier
	s_setprio 0
	s_cbranch_scc0 .LBB0_384
	s_waitcnt vmcnt(0)
	v_add_f32_e32 v52, v52, v53
	v_add_f32_e32 v53, v54, v55
	v_add_f32_e32 v52, v52, v53
	v_mov_b32_e32 v53, v52
	s_nop 1
	v_permlane16_swap_b32_e32 v52, v53
	v_add_f32_e32 v52, v52, v53
	v_mov_b32_e32 v53, v52
	s_nop 1
	v_permlane32_swap_b32_e32 v52, v53
	v_add_f32_e32 v52, v52, v53
	v_fmamk_f32 v52, v52, 0x3a800000, v207
	s_mul_i32 s42, s65, 0xc0
	v_rsq_f32_e32 v52, v52
	v_add_f32_e32 v36, v36, v37
	v_add_f32_e32 v37, v38, v39
	s_add_i32 s42, s42, s19
	v_add_f32_e32 v44, v44, v45
	v_add_f32_e32 v45, v46, v47
	v_add_f32_e32 v36, v36, v37
	s_cmpk_lt_u32 s42, 0x2000
	v_add_f32_e32 v44, v44, v45
	v_mov_b32_e32 v37, v36
	v_lshl_or_b32 v154, s64, 8, v158
	s_cselect_b32 s43, 1, 2
	v_or_b32_e32 v160, s42, v156
	v_mov_b32_e32 v45, v44
	v_permlane16_swap_b32_e32 v36, v37
	v_add_f32_e32 v32, v32, v33
	v_add_f32_e32 v33, v34, v35
	v_mov_b64_e32 v[34:35], s[46:47]
	v_mov_b32_e32 v96, s43
	v_permlane16_swap_b32_e32 v44, v45
	v_add_f32_e32 v38, v36, v37
	v_add_f32_e32 v36, v40, v41
	v_add_f32_e32 v37, v42, v43
	v_ashrrev_i32_e32 v155, 31, v154
	v_mad_i64_i32 v[34:35], s[42:43], v160, s25, v[34:35]
	v_pk_fma_f32 v[42:43], v[136:137], v[52:53], v[6:7] op_sel_hi:[1,0,1]
	v_pk_fma_f32 v[40:41], v[134:135], v[52:53], v[4:5] op_sel_hi:[1,0,1]
	v_add_f32_e32 v46, v44, v45
	v_add_f32_e32 v44, v48, v49
	v_add_f32_e32 v45, v50, v51
	v_lshl_add_u64 v[34:35], v[154:155], 1, v[34:35]
	v_pk_fma_f32 v[48:49], v[132:133], v[52:53], v[2:3] op_sel_hi:[1,0,1]
	v_pk_fma_f32 v[50:51], v[130:131], v[52:53], v[0:1] op_sel_hi:[1,0,1]
	v_cvt_pk_bf16_f32 v40, v40, v41
	v_cvt_pk_bf16_f32 v41, v42, v43
	v_add_f32_e32 v44, v44, v45
	v_cvt_pk_bf16_f32 v42, v50, v51
	v_cvt_pk_bf16_f32 v43, v48, v49
	v_add_f32_e32 v36, v36, v37
	v_add_f32_e32 v32, v32, v33
	global_store_dwordx4 v[34:35], v[40:43], off
	v_cmp_lt_i32_e32 vcc, s23, v160
	v_mov_b32_e32 v45, v44
	v_pk_fma_f32 v[42:43], v[128:129], v[52:53], v[14:15] op_sel_hi:[1,0,1]
	v_pk_fma_f32 v[40:41], v[126:127], v[52:53], v[12:13] op_sel_hi:[1,0,1]
	v_mov_b32_e32 v37, v36
	v_mov_b32_e32 v33, v32
	v_pk_fma_f32 v[48:49], v[124:125], v[52:53], v[10:11] op_sel_hi:[1,0,1]
	v_pk_fma_f32 v[50:51], v[122:123], v[52:53], v[8:9] op_sel_hi:[1,0,1]
	v_cvt_pk_bf16_f32 v40, v40, v41
	v_cvt_pk_bf16_f32 v41, v42, v43
	v_cndmask_b32_e32 v96, 0, v96, vcc
	v_cvt_pk_bf16_f32 v42, v50, v51
	v_cvt_pk_bf16_f32 v43, v48, v49
	global_store_dwordx4 v[34:35], v[40:43], off offset:256
	v_add_u32_e32 v34, 16, v160
	v_permlane16_swap_b32_e32 v44, v45
	v_permlane16_swap_b32_e32 v36, v37
	v_permlane16_swap_b32_e32 v32, v33
	v_cmp_gt_u32_e32 vcc, s24, v34
	v_add_f32_e32 v44, v44, v45
	v_add_f32_e32 v36, v36, v37
	v_add_f32_e32 v32, v32, v33
	v_cndmask_b32_e64 v35, 2, 1, vcc
	v_cmp_lt_i32_e32 vcc, s26, v160
	v_mov_b32_e32 v47, v46
	v_mov_b32_e32 v45, v44
	v_mov_b32_e32 v39, v38
	v_mov_b32_e32 v37, v36
	v_mov_b32_e32 v33, v32
	v_cndmask_b32_e32 v35, 0, v35, vcc
	v_permlane32_swap_b32_e32 v46, v47
	v_permlane32_swap_b32_e32 v44, v45
	v_permlane32_swap_b32_e32 v38, v39
	v_permlane32_swap_b32_e32 v36, v37
	v_permlane32_swap_b32_e32 v32, v33
	v_cmp_ne_u32_e32 vcc, v35, v96
	s_and_saveexec_b64 s[42:43], vcc
	s_cbranch_execz .LBB0_387
	v_mul_u32_u24_e32 v0, 0x7600, v35
	v_lshlrev_b32_e32 v96, 2, v0
	v_lshl_add_u64 v[0:1], s[44:45], 0, v[96:97]
	v_lshl_add_u64 v[12:13], v[154:155], 2, v[0:1]
	global_load_dwordx4 v[0:3], v[12:13], off offset:16
	global_load_dwordx4 v[4:7], v[12:13], off
	global_load_dwordx4 v[8:11], v[12:13], off offset:528
	s_nop 0
	global_load_dwordx4 v[12:15], v[12:13], off offset:512
	v_mov_b32_e32 v96, v35

.LBB0_464:
	s_ashr_i32 s51, s50, 31
	s_lshl_b64 s[54:55], s[50:51], 19
	s_add_u32 s54, s10, s54
	s_addc_u32 s55, s11, s55
	s_and_b64 s[42:43], s[42:43], exec
	s_cselect_b32 s51, s55, s59
	s_cselect_b32 s68, s54, s58
	s_add_u32 s42, s60, 0x30080
	s_addc_u32 s43, s61, 0
	s_add_u32 s69, s58, 0x100
	s_addc_u32 s70, s59, 0
	s_mov_b32 s71, -2
	s_add_u32 s58, s42, 0xfffd0080
	s_addc_u32 s59, s43, -1
	s_add_i32 s72, 0, 0x10000
	v_add_u32_e32 v96, s72, v163
	ds_read_b128 v[154:157], v96
	ds_read_b128 v[170:173], v96 offset:1024
	ds_read_b128 v[174:177], v96 offset:2048
	ds_read_b128 v[182:185], v96 offset:3072
	s_cmp_eq_u32 s71, 12
	s_cselect_b32 s61, s53, s59
	s_cselect_b32 s60, s52, s58
	s_cselect_b32 s59, s51, s70
	s_cselect_b32 s58, s68, s69
	s_add_i32 m0, s27, 0xc000
	ds_read_b128 v[186:189], v168
	ds_read_b128 v[190:193], v168 offset:1024
	ds_read_b128 v[194:197], v168 offset:2048
	ds_read_b128 v[198:201], v168 offset:3072
	ds_read_b128 v[224:227], v168 offset:4096
	ds_read_b128 v[228:231], v168 offset:5120
	global_load_lds_dwordx4 v150, s[42:43]
	s_add_i32 m0, s27, 0xe000
	s_mov_b64 exec, s[98:99]
	global_load_lds_dwordx4 v152, s[42:43]
	s_mov_b64 exec, -1
	s_add_i32 s80, 0, 0x14000
	s_add_i32 s72, s72, s18
	v_add_u32_e32 v96, s80, v163
	v_lshl_add_u64 v[160:161], s[58:59], 0, v[140:141]
	ds_read_b128 v[232:235], v96
	ds_read_b128 v[236:239], v96 offset:1024
	ds_read_b128 v[240:243], v96 offset:2048
	ds_read_b128 v[244:247], v96 offset:3072
	v_lshl_add_u64 v[164:165], s[58:59], 0, v[144:145]
	s_waitcnt vmcnt(8)
	s_waitcnt lgkmcnt(4)
	s_setprio 1
	s_barrier
	s_waitcnt lgkmcnt(0)
	v_mfma_f32_16x16x32_bf16 v[134:137], v[154:157], v[186:189], 0
	v_mfma_f32_16x16x32_bf16 v[130:133], v[174:177], v[186:189], 0
	v_mfma_f32_16x16x32_bf16 v[92:95], v[154:157], v[194:197], 0
	v_mfma_f32_16x16x32_bf16 v[88:91], v[174:177], v[194:197], 0
	v_mfma_f32_16x16x32_bf16 v[76:79], v[154:157], v[224:227], 0
	v_mfma_f32_16x16x32_bf16 v[72:75], v[174:177], v[224:227], 0
	v_mfma_f32_16x16x32_bf16 v[134:137], v[170:173], v[190:193], v[134:137]
	v_mfma_f32_16x16x32_bf16 v[130:133], v[182:185], v[190:193], v[130:133]
	v_mfma_f32_16x16x32_bf16 v[92:95], v[170:173], v[198:201], v[92:95]
	v_mfma_f32_16x16x32_bf16 v[88:91], v[182:185], v[198:201], v[88:91]
	v_mfma_f32_16x16x32_bf16 v[76:79], v[170:173], v[228:231], v[76:79]
	v_mfma_f32_16x16x32_bf16 v[72:75], v[182:185], v[228:231], v[72:75]
	v_mfma_f32_16x16x32_bf16 v[110:113], v[232:235], v[186:189], 0
	v_mfma_f32_16x16x32_bf16 v[98:101], v[240:243], v[186:189], 0
	v_mfma_f32_16x16x32_bf16 v[84:87], v[232:235], v[194:197], 0
	s_mov_b32 m0, s27
	v_mfma_f32_16x16x32_bf16 v[80:83], v[240:243], v[194:197], 0
	v_lshl_add_u64 v[202:203], s[60:61], 0, v[138:139]
	v_mfma_f32_16x16x32_bf16 v[68:71], v[232:235], v[224:227], 0
	v_mfma_f32_16x16x32_bf16 v[64:67], v[240:243], v[224:227], 0
	v_mfma_f32_16x16x32_bf16 v[110:113], v[236:239], v[190:193], v[110:113]
	v_mfma_f32_16x16x32_bf16 v[98:101], v[244:247], v[190:193], v[98:101]
	v_mfma_f32_16x16x32_bf16 v[84:87], v[236:239], v[198:201], v[84:87]
	v_mfma_f32_16x16x32_bf16 v[80:83], v[244:247], v[198:201], v[80:83]
	v_mfma_f32_16x16x32_bf16 v[68:71], v[236:239], v[228:231], v[68:71]
	v_mfma_f32_16x16x32_bf16 v[64:67], v[244:247], v[228:231], v[64:67]
	s_barrier
	s_setprio 0
	s_mov_b32 m0, s72
	s_nop 0
	global_load_lds_dwordx4 v140, s[58:59]
	s_add_i32 m0, s72, 0x2000
	s_nop 0
	global_load_lds_dwordx4 v144, s[58:59]
	s_mov_b32 m0, s27
	ds_read_b128 v[186:189], v168 offset:16384
	ds_read_b128 v[190:193], v168 offset:17408
	ds_read_b128 v[194:197], v168 offset:18432
	ds_read_b128 v[198:201], v168 offset:19456
	ds_read_b128 v[224:227], v168 offset:20480
	ds_read_b128 v[228:231], v168 offset:21504
	global_load_lds_dwordx4 v138, s[60:61]
	v_lshl_add_u64 v[248:249], s[60:61], 0, v[142:143]
	s_mov_b32 m0, s28
	s_mov_b64 exec, s[98:99]
	global_load_lds_dwordx4 v142, s[60:61]
	s_mov_b64 exec, -1
	s_add_u32 s78, s58, 0x40000
	s_addc_u32 s79, s59, 0
	s_add_i32 s72, s80, s18
	s_mov_b32 m0, s72
	s_nop 0
	global_load_lds_dwordx4 v140, s[78:79]
	s_add_i32 m0, s72, 0x2000
	s_nop 0
	global_load_lds_dwordx4 v144, s[78:79]
	s_waitcnt vmcnt(8)
	s_waitcnt lgkmcnt(0)
	s_setprio 1
	s_barrier
	v_mfma_f32_16x16x32_bf16 v[60:63], v[154:157], v[186:189], 0
	v_mfma_f32_16x16x32_bf16 v[56:59], v[174:177], v[186:189], 0
	v_mfma_f32_16x16x32_bf16 v[44:47], v[154:157], v[194:197], 0
	v_mfma_f32_16x16x32_bf16 v[40:43], v[174:177], v[194:197], 0
	v_mfma_f32_16x16x32_bf16 v[28:31], v[154:157], v[224:227], 0
	v_mfma_f32_16x16x32_bf16 v[24:27], v[174:177], v[224:227], 0
	v_mfma_f32_16x16x32_bf16 v[60:63], v[170:173], v[190:193], v[60:63]
	v_mfma_f32_16x16x32_bf16 v[56:59], v[182:185], v[190:193], v[56:59]
	v_mfma_f32_16x16x32_bf16 v[44:47], v[170:173], v[198:201], v[44:47]
	v_mfma_f32_16x16x32_bf16 v[40:43], v[182:185], v[198:201], v[40:43]
	v_mfma_f32_16x16x32_bf16 v[28:31], v[170:173], v[228:231], v[28:31]
	v_mfma_f32_16x16x32_bf16 v[24:27], v[182:185], v[228:231], v[24:27]
	v_mfma_f32_16x16x32_bf16 v[52:55], v[232:235], v[186:189], 0
	v_mfma_f32_16x16x32_bf16 v[48:51], v[240:243], v[186:189], 0
	v_mfma_f32_16x16x32_bf16 v[36:39], v[232:235], v[194:197], 0
	s_add_i32 s72, 0, 0x18000
	v_mfma_f32_16x16x32_bf16 v[32:35], v[240:243], v[194:197], 0
	v_add_u32_e32 v96, s72, v163
	v_mfma_f32_16x16x32_bf16 v[20:23], v[232:235], v[224:227], 0
	v_mfma_f32_16x16x32_bf16 v[16:19], v[240:243], v[224:227], 0
	v_mfma_f32_16x16x32_bf16 v[52:55], v[236:239], v[190:193], v[52:55]
	v_mfma_f32_16x16x32_bf16 v[48:51], v[244:247], v[190:193], v[48:51]
	v_mfma_f32_16x16x32_bf16 v[36:39], v[236:239], v[198:201], v[36:39]
	v_mfma_f32_16x16x32_bf16 v[32:35], v[244:247], v[198:201], v[32:35]
	v_mfma_f32_16x16x32_bf16 v[20:23], v[236:239], v[228:231], v[20:23]
	v_mfma_f32_16x16x32_bf16 v[16:19], v[244:247], v[228:231], v[16:19]
	s_barrier
	s_setprio 0
	ds_read_b128 v[154:157], v96
	ds_read_b128 v[170:173], v96 offset:1024
	ds_read_b128 v[174:177], v96 offset:2048
	ds_read_b128 v[182:185], v96 offset:3072
	s_add_u32 s60, s60, 0x30000
	s_addc_u32 s61, s61, 0
	s_mov_b32 m0, s37
	ds_read_b128 v[186:189], v168 offset:32768
	ds_read_b128 v[190:193], v168 offset:33792
	ds_read_b128 v[194:197], v168 offset:34816
	ds_read_b128 v[198:201], v168 offset:35840
	ds_read_b128 v[224:227], v168 offset:36864
	ds_read_b128 v[228:231], v168 offset:37888
	global_load_lds_dwordx4 v138, s[60:61]
	s_mov_b32 m0, s57
	s_mov_b64 exec, s[98:99]
	global_load_lds_dwordx4 v142, s[60:61]
	s_mov_b64 exec, -1
	s_add_i32 s60, 0, 0x1c000
	s_add_i32 s61, s72, s18
	v_add_u32_e32 v96, s60, v163
	ds_read_b128 v[232:235], v96
	ds_read_b128 v[236:239], v96 offset:1024
	ds_read_b128 v[240:243], v96 offset:2048
	ds_read_b128 v[244:247], v96 offset:3072
	s_waitcnt vmcnt(8)
	s_waitcnt lgkmcnt(4)
	s_setprio 1
	s_barrier
	s_waitcnt lgkmcnt(0)
	v_mfma_f32_16x16x32_bf16 v[134:137], v[154:157], v[186:189], v[134:137]
	v_mfma_f32_16x16x32_bf16 v[130:133], v[174:177], v[186:189], v[130:133]
	v_mfma_f32_16x16x32_bf16 v[92:95], v[154:157], v[194:197], v[92:95]
	v_mfma_f32_16x16x32_bf16 v[88:91], v[174:177], v[194:197], v[88:91]
	v_mfma_f32_16x16x32_bf16 v[76:79], v[154:157], v[224:227], v[76:79]
	v_mfma_f32_16x16x32_bf16 v[72:75], v[174:177], v[224:227], v[72:75]
	v_mfma_f32_16x16x32_bf16 v[134:137], v[170:173], v[190:193], v[134:137]
	v_mfma_f32_16x16x32_bf16 v[130:133], v[182:185], v[190:193], v[130:133]
	v_mfma_f32_16x16x32_bf16 v[92:95], v[170:173], v[198:201], v[92:95]
	v_mfma_f32_16x16x32_bf16 v[88:91], v[182:185], v[198:201], v[88:91]
	v_mfma_f32_16x16x32_bf16 v[76:79], v[170:173], v[228:231], v[76:79]
	v_mfma_f32_16x16x32_bf16 v[72:75], v[182:185], v[228:231], v[72:75]
	v_mfma_f32_16x16x32_bf16 v[110:113], v[232:235], v[186:189], v[110:113]
	v_mfma_f32_16x16x32_bf16 v[98:101], v[240:243], v[186:189], v[98:101]
	v_mfma_f32_16x16x32_bf16 v[84:87], v[232:235], v[194:197], v[84:87]
	s_mov_b32 m0, s62
	v_mfma_f32_16x16x32_bf16 v[80:83], v[240:243], v[194:197], v[80:83]
	v_lshl_add_u64 v[160:161], v[202:203], 0, s[6:7]
	v_mfma_f32_16x16x32_bf16 v[68:71], v[232:235], v[224:227], v[68:71]
	v_mfma_f32_16x16x32_bf16 v[64:67], v[240:243], v[224:227], v[64:67]
	v_mfma_f32_16x16x32_bf16 v[110:113], v[236:239], v[190:193], v[110:113]
	v_mfma_f32_16x16x32_bf16 v[98:101], v[244:247], v[190:193], v[98:101]
	v_mfma_f32_16x16x32_bf16 v[84:87], v[236:239], v[198:201], v[84:87]
	v_mfma_f32_16x16x32_bf16 v[80:83], v[244:247], v[198:201], v[80:83]
	v_mfma_f32_16x16x32_bf16 v[68:71], v[236:239], v[228:231], v[68:71]
	v_mfma_f32_16x16x32_bf16 v[64:67], v[244:247], v[228:231], v[64:67]
	s_barrier
	s_setprio 0
	v_lshl_add_u64 v[160:161], s[58:59], 0, v[140:141]
	v_lshl_add_u64 v[160:161], v[160:161], 0, s[6:7]
	s_mov_b32 m0, s61
	s_nop 0
	global_load_lds_dwordx4 v[160:161], off
	v_lshl_add_u64 v[160:161], v[164:165], 0, s[6:7]
	s_add_i32 m0, s61, 0x2000
	s_nop 0
	global_load_lds_dwordx4 v[160:161], off
	s_mov_b32 m0, s62
	v_lshl_add_u64 v[160:161], v[202:203], 0, s[6:7]
	ds_read_b128 v[186:189], v168 offset:49152
	ds_read_b128 v[190:193], v168 offset:50176
	ds_read_b128 v[194:197], v168 offset:51200
	ds_read_b128 v[198:201], v168 offset:52224
	ds_read_b128 v[224:227], v168 offset:53248
	ds_read_b128 v[228:231], v168 offset:54272
	global_load_lds_dwordx4 v[160:161], off
	v_lshl_add_u64 v[160:161], v[248:249], 0, s[6:7]
	s_mov_b32 m0, s63
	s_mov_b64 exec, s[98:99]
	global_load_lds_dwordx4 v[160:161], off
	s_mov_b64 exec, -1
	s_add_u32 s58, s58, 0x40080
	s_addc_u32 s59, s59, 0
	s_add_i32 s60, s60, s18
	s_mov_b32 m0, s60
	s_nop 0
	global_load_lds_dwordx4 v140, s[58:59]
	s_add_i32 m0, s60, 0x2000
	s_nop 0
	global_load_lds_dwordx4 v144, s[58:59]
	s_waitcnt vmcnt(8)
	s_waitcnt lgkmcnt(0)
	s_setprio 1
	s_barrier
	v_mfma_f32_16x16x32_bf16 v[60:63], v[154:157], v[186:189], v[60:63]
	v_mfma_f32_16x16x32_bf16 v[56:59], v[174:177], v[186:189], v[56:59]
	v_mfma_f32_16x16x32_bf16 v[44:47], v[154:157], v[194:197], v[44:47]
	v_mfma_f32_16x16x32_bf16 v[40:43], v[174:177], v[194:197], v[40:43]
	v_mfma_f32_16x16x32_bf16 v[28:31], v[154:157], v[224:227], v[28:31]
	v_mfma_f32_16x16x32_bf16 v[24:27], v[174:177], v[224:227], v[24:27]
	v_mfma_f32_16x16x32_bf16 v[60:63], v[170:173], v[190:193], v[60:63]
	v_mfma_f32_16x16x32_bf16 v[56:59], v[182:185], v[190:193], v[56:59]
	v_mfma_f32_16x16x32_bf16 v[44:47], v[170:173], v[198:201], v[44:47]
	v_mfma_f32_16x16x32_bf16 v[40:43], v[182:185], v[198:201], v[40:43]
	v_mfma_f32_16x16x32_bf16 v[28:31], v[170:173], v[228:231], v[28:31]
	v_mfma_f32_16x16x32_bf16 v[24:27], v[182:185], v[228:231], v[24:27]
	v_mfma_f32_16x16x32_bf16 v[52:55], v[232:235], v[186:189], v[52:55]
	v_mfma_f32_16x16x32_bf16 v[48:51], v[240:243], v[186:189], v[48:51]
	v_mfma_f32_16x16x32_bf16 v[36:39], v[232:235], v[194:197], v[36:39]
	s_add_i32 s71, s71, 2
	v_mfma_f32_16x16x32_bf16 v[32:35], v[240:243], v[194:197], v[32:35]
	s_add_u32 s42, s42, 0x100
	v_mfma_f32_16x16x32_bf16 v[20:23], v[232:235], v[224:227], v[20:23]
	s_addc_u32 s43, s43, 0
	v_mfma_f32_16x16x32_bf16 v[16:19], v[240:243], v[224:227], v[16:19]
	s_add_u32 s69, s69, 0x100
	v_mfma_f32_16x16x32_bf16 v[52:55], v[236:239], v[190:193], v[52:55]
	s_addc_u32 s70, s70, 0
	v_mfma_f32_16x16x32_bf16 v[48:51], v[244:247], v[190:193], v[48:51]
	s_cmp_gt_u32 s71, 13
	v_mfma_f32_16x16x32_bf16 v[36:39], v[236:239], v[198:201], v[36:39]
	v_mfma_f32_16x16x32_bf16 v[32:35], v[244:247], v[198:201], v[32:35]
	v_mfma_f32_16x16x32_bf16 v[20:23], v[236:239], v[228:231], v[20:23]
	v_mfma_f32_16x16x32_bf16 v[16:19], v[244:247], v[228:231], v[16:19]
	s_barrier
	s_setprio 0
.LBB0_465:
	s_add_u32 s58, s42, 0xfffd0080
	s_addc_u32 s59, s43, -1
	s_add_i32 s72, 0, 0x10000
	v_add_u32_e32 v96, s72, v163
	ds_read_b128 v[154:157], v96
	ds_read_b128 v[170:173], v96 offset:1024
	ds_read_b128 v[174:177], v96 offset:2048
	ds_read_b128 v[182:185], v96 offset:3072
	s_cmp_eq_u32 s71, 12
	s_cselect_b32 s61, s53, s59
	s_cselect_b32 s60, s52, s58
	s_cselect_b32 s59, s51, s70
	s_cselect_b32 s58, s68, s69
	s_add_i32 m0, s27, 0xc000
	ds_read_b128 v[186:189], v168
	ds_read_b128 v[190:193], v168 offset:1024
	ds_read_b128 v[194:197], v168 offset:2048
	ds_read_b128 v[198:201], v168 offset:3072
	ds_read_b128 v[224:227], v168 offset:4096
	ds_read_b128 v[228:231], v168 offset:5120
	global_load_lds_dwordx4 v150, s[42:43]
	s_add_i32 m0, s27, 0xe000
	s_mov_b64 exec, s[98:99]
	global_load_lds_dwordx4 v152, s[42:43]
	s_mov_b64 exec, -1
	s_add_i32 s80, 0, 0x14000
	s_add_i32 s72, s72, s18
	v_add_u32_e32 v96, s80, v163
	v_lshl_add_u64 v[160:161], s[58:59], 0, v[140:141]
	ds_read_b128 v[232:235], v96
	ds_read_b128 v[236:239], v96 offset:1024
	ds_read_b128 v[240:243], v96 offset:2048
	ds_read_b128 v[244:247], v96 offset:3072
	v_lshl_add_u64 v[164:165], s[58:59], 0, v[144:145]
	s_waitcnt vmcnt(8)
	s_waitcnt lgkmcnt(4)
	s_setprio 1
	s_barrier
	s_waitcnt lgkmcnt(0)
	v_mfma_f32_16x16x32_bf16 v[134:137], v[154:157], v[186:189], v[134:137]
	v_mfma_f32_16x16x32_bf16 v[130:133], v[174:177], v[186:189], v[130:133]
	v_mfma_f32_16x16x32_bf16 v[92:95], v[154:157], v[194:197], v[92:95]
	v_mfma_f32_16x16x32_bf16 v[88:91], v[174:177], v[194:197], v[88:91]
	v_mfma_f32_16x16x32_bf16 v[76:79], v[154:157], v[224:227], v[76:79]
	v_mfma_f32_16x16x32_bf16 v[72:75], v[174:177], v[224:227], v[72:75]
	v_mfma_f32_16x16x32_bf16 v[134:137], v[170:173], v[190:193], v[134:137]
	v_mfma_f32_16x16x32_bf16 v[130:133], v[182:185], v[190:193], v[130:133]
	v_mfma_f32_16x16x32_bf16 v[92:95], v[170:173], v[198:201], v[92:95]
	v_mfma_f32_16x16x32_bf16 v[88:91], v[182:185], v[198:201], v[88:91]
	v_mfma_f32_16x16x32_bf16 v[76:79], v[170:173], v[228:231], v[76:79]
	v_mfma_f32_16x16x32_bf16 v[72:75], v[182:185], v[228:231], v[72:75]
	v_mfma_f32_16x16x32_bf16 v[110:113], v[232:235], v[186:189], v[110:113]
	v_mfma_f32_16x16x32_bf16 v[98:101], v[240:243], v[186:189], v[98:101]
	v_mfma_f32_16x16x32_bf16 v[84:87], v[232:235], v[194:197], v[84:87]
	s_mov_b32 m0, s27
	v_mfma_f32_16x16x32_bf16 v[80:83], v[240:243], v[194:197], v[80:83]
	v_lshl_add_u64 v[202:203], s[60:61], 0, v[138:139]
	v_mfma_f32_16x16x32_bf16 v[68:71], v[232:235], v[224:227], v[68:71]
	v_mfma_f32_16x16x32_bf16 v[64:67], v[240:243], v[224:227], v[64:67]
	v_mfma_f32_16x16x32_bf16 v[110:113], v[236:239], v[190:193], v[110:113]
	v_mfma_f32_16x16x32_bf16 v[98:101], v[244:247], v[190:193], v[98:101]
	v_mfma_f32_16x16x32_bf16 v[84:87], v[236:239], v[198:201], v[84:87]
	v_mfma_f32_16x16x32_bf16 v[80:83], v[244:247], v[198:201], v[80:83]
	v_mfma_f32_16x16x32_bf16 v[68:71], v[236:239], v[228:231], v[68:71]
	v_mfma_f32_16x16x32_bf16 v[64:67], v[244:247], v[228:231], v[64:67]
	s_barrier
	s_setprio 0
	s_mov_b32 m0, s72
	s_nop 0
	global_load_lds_dwordx4 v140, s[58:59]
	s_add_i32 m0, s72, 0x2000
	s_nop 0
	global_load_lds_dwordx4 v144, s[58:59]
	s_mov_b32 m0, s27
	ds_read_b128 v[186:189], v168 offset:16384
	ds_read_b128 v[190:193], v168 offset:17408
	ds_read_b128 v[194:197], v168 offset:18432
	ds_read_b128 v[198:201], v168 offset:19456
	ds_read_b128 v[224:227], v168 offset:20480
	ds_read_b128 v[228:231], v168 offset:21504
	global_load_lds_dwordx4 v138, s[60:61]
	v_lshl_add_u64 v[248:249], s[60:61], 0, v[142:143]
	s_mov_b32 m0, s28
	s_mov_b64 exec, s[98:99]
	global_load_lds_dwordx4 v142, s[60:61]
	s_mov_b64 exec, -1
	s_add_u32 s78, s58, 0x40000
	s_addc_u32 s79, s59, 0
	s_add_i32 s72, s80, s18
	s_mov_b32 m0, s72
	s_nop 0
	global_load_lds_dwordx4 v140, s[78:79]
	s_add_i32 m0, s72, 0x2000
	s_nop 0
	global_load_lds_dwordx4 v144, s[78:79]
	s_waitcnt vmcnt(8)
	s_waitcnt lgkmcnt(0)
	s_setprio 1
	s_barrier
	v_mfma_f32_16x16x32_bf16 v[60:63], v[154:157], v[186:189], v[60:63]
	v_mfma_f32_16x16x32_bf16 v[56:59], v[174:177], v[186:189], v[56:59]
	v_mfma_f32_16x16x32_bf16 v[44:47], v[154:157], v[194:197], v[44:47]
	v_mfma_f32_16x16x32_bf16 v[40:43], v[174:177], v[194:197], v[40:43]
	v_mfma_f32_16x16x32_bf16 v[28:31], v[154:157], v[224:227], v[28:31]
	v_mfma_f32_16x16x32_bf16 v[24:27], v[174:177], v[224:227], v[24:27]
	v_mfma_f32_16x16x32_bf16 v[60:63], v[170:173], v[190:193], v[60:63]
	v_mfma_f32_16x16x32_bf16 v[56:59], v[182:185], v[190:193], v[56:59]
	v_mfma_f32_16x16x32_bf16 v[44:47], v[170:173], v[198:201], v[44:47]
	v_mfma_f32_16x16x32_bf16 v[40:43], v[182:185], v[198:201], v[40:43]
	v_mfma_f32_16x16x32_bf16 v[28:31], v[170:173], v[228:231], v[28:31]
	v_mfma_f32_16x16x32_bf16 v[24:27], v[182:185], v[228:231], v[24:27]
	v_mfma_f32_16x16x32_bf16 v[52:55], v[232:235], v[186:189], v[52:55]
	v_mfma_f32_16x16x32_bf16 v[48:51], v[240:243], v[186:189], v[48:51]
	v_mfma_f32_16x16x32_bf16 v[36:39], v[232:235], v[194:197], v[36:39]
	s_add_i32 s72, 0, 0x18000
	v_mfma_f32_16x16x32_bf16 v[32:35], v[240:243], v[194:197], v[32:35]
	v_add_u32_e32 v96, s72, v163
	v_mfma_f32_16x16x32_bf16 v[20:23], v[232:235], v[224:227], v[20:23]
	v_mfma_f32_16x16x32_bf16 v[16:19], v[240:243], v[224:227], v[16:19]
	v_mfma_f32_16x16x32_bf16 v[52:55], v[236:239], v[190:193], v[52:55]
	v_mfma_f32_16x16x32_bf16 v[48:51], v[244:247], v[190:193], v[48:51]
	v_mfma_f32_16x16x32_bf16 v[36:39], v[236:239], v[198:201], v[36:39]
	v_mfma_f32_16x16x32_bf16 v[32:35], v[244:247], v[198:201], v[32:35]
	v_mfma_f32_16x16x32_bf16 v[20:23], v[236:239], v[228:231], v[20:23]
	v_mfma_f32_16x16x32_bf16 v[16:19], v[244:247], v[228:231], v[16:19]
	s_barrier
	s_setprio 0
	ds_read_b128 v[154:157], v96
	ds_read_b128 v[170:173], v96 offset:1024
	ds_read_b128 v[174:177], v96 offset:2048
	ds_read_b128 v[182:185], v96 offset:3072
	s_add_u32 s60, s60, 0x30000
	s_addc_u32 s61, s61, 0
	s_mov_b32 m0, s37
	ds_read_b128 v[186:189], v168 offset:32768
	ds_read_b128 v[190:193], v168 offset:33792
	ds_read_b128 v[194:197], v168 offset:34816
	ds_read_b128 v[198:201], v168 offset:35840
	ds_read_b128 v[224:227], v168 offset:36864
	ds_read_b128 v[228:231], v168 offset:37888
	global_load_lds_dwordx4 v138, s[60:61]
	s_mov_b32 m0, s57
	s_mov_b64 exec, s[98:99]
	global_load_lds_dwordx4 v142, s[60:61]
	s_mov_b64 exec, -1
	s_add_i32 s60, 0, 0x1c000
	s_add_i32 s61, s72, s18
	v_add_u32_e32 v96, s60, v163
	ds_read_b128 v[232:235], v96
	ds_read_b128 v[236:239], v96 offset:1024
	ds_read_b128 v[240:243], v96 offset:2048
	ds_read_b128 v[244:247], v96 offset:3072
	s_waitcnt vmcnt(8)
	s_waitcnt lgkmcnt(4)
	s_setprio 1
	s_barrier
	s_waitcnt lgkmcnt(0)
	v_mfma_f32_16x16x32_bf16 v[134:137], v[154:157], v[186:189], v[134:137]
	v_mfma_f32_16x16x32_bf16 v[130:133], v[174:177], v[186:189], v[130:133]
	v_mfma_f32_16x16x32_bf16 v[92:95], v[154:157], v[194:197], v[92:95]
	v_mfma_f32_16x16x32_bf16 v[88:91], v[174:177], v[194:197], v[88:91]
	v_mfma_f32_16x16x32_bf16 v[76:79], v[154:157], v[224:227], v[76:79]
	v_mfma_f32_16x16x32_bf16 v[72:75], v[174:177], v[224:227], v[72:75]
	v_mfma_f32_16x16x32_bf16 v[134:137], v[170:173], v[190:193], v[134:137]
	v_mfma_f32_16x16x32_bf16 v[130:133], v[182:185], v[190:193], v[130:133]
	v_mfma_f32_16x16x32_bf16 v[92:95], v[170:173], v[198:201], v[92:95]
	v_mfma_f32_16x16x32_bf16 v[88:91], v[182:185], v[198:201], v[88:91]
	v_mfma_f32_16x16x32_bf16 v[76:79], v[170:173], v[228:231], v[76:79]
	v_mfma_f32_16x16x32_bf16 v[72:75], v[182:185], v[228:231], v[72:75]
	v_mfma_f32_16x16x32_bf16 v[110:113], v[232:235], v[186:189], v[110:113]
	v_mfma_f32_16x16x32_bf16 v[98:101], v[240:243], v[186:189], v[98:101]
	v_mfma_f32_16x16x32_bf16 v[84:87], v[232:235], v[194:197], v[84:87]
	s_mov_b32 m0, s62
	v_mfma_f32_16x16x32_bf16 v[80:83], v[240:243], v[194:197], v[80:83]
	v_lshl_add_u64 v[160:161], v[202:203], 0, s[6:7]
	v_mfma_f32_16x16x32_bf16 v[68:71], v[232:235], v[224:227], v[68:71]
	v_mfma_f32_16x16x32_bf16 v[64:67], v[240:243], v[224:227], v[64:67]
	v_mfma_f32_16x16x32_bf16 v[110:113], v[236:239], v[190:193], v[110:113]
	v_mfma_f32_16x16x32_bf16 v[98:101], v[244:247], v[190:193], v[98:101]
	v_mfma_f32_16x16x32_bf16 v[84:87], v[236:239], v[198:201], v[84:87]
	v_mfma_f32_16x16x32_bf16 v[80:83], v[244:247], v[198:201], v[80:83]
	v_mfma_f32_16x16x32_bf16 v[68:71], v[236:239], v[228:231], v[68:71]
	v_mfma_f32_16x16x32_bf16 v[64:67], v[244:247], v[228:231], v[64:67]
	s_barrier
	s_setprio 0
	v_lshl_add_u64 v[160:161], s[58:59], 0, v[140:141]
	v_lshl_add_u64 v[160:161], v[160:161], 0, s[6:7]
	s_mov_b32 m0, s61
	s_nop 0
	global_load_lds_dwordx4 v[160:161], off
	v_lshl_add_u64 v[160:161], v[164:165], 0, s[6:7]
	s_add_i32 m0, s61, 0x2000
	s_nop 0
	global_load_lds_dwordx4 v[160:161], off
	s_mov_b32 m0, s62
	v_lshl_add_u64 v[160:161], v[202:203], 0, s[6:7]
	ds_read_b128 v[186:189], v168 offset:49152
	ds_read_b128 v[190:193], v168 offset:50176
	ds_read_b128 v[194:197], v168 offset:51200
	ds_read_b128 v[198:201], v168 offset:52224
	ds_read_b128 v[224:227], v168 offset:53248
	ds_read_b128 v[228:231], v168 offset:54272
	global_load_lds_dwordx4 v[160:161], off
	v_lshl_add_u64 v[160:161], v[248:249], 0, s[6:7]
	s_mov_b32 m0, s63
	s_mov_b64 exec, s[98:99]
	global_load_lds_dwordx4 v[160:161], off
	s_mov_b64 exec, -1
	s_add_u32 s58, s58, 0x40080
	s_addc_u32 s59, s59, 0
	s_add_i32 s60, s60, s18
	s_mov_b32 m0, s60
	s_nop 0
	global_load_lds_dwordx4 v140, s[58:59]
	s_add_i32 m0, s60, 0x2000
	s_nop 0
	global_load_lds_dwordx4 v144, s[58:59]
	s_waitcnt vmcnt(8)
	s_waitcnt lgkmcnt(0)
	s_setprio 1
	s_barrier
	v_mfma_f32_16x16x32_bf16 v[60:63], v[154:157], v[186:189], v[60:63]
	v_mfma_f32_16x16x32_bf16 v[56:59], v[174:177], v[186:189], v[56:59]
	v_mfma_f32_16x16x32_bf16 v[44:47], v[154:157], v[194:197], v[44:47]
	v_mfma_f32_16x16x32_bf16 v[40:43], v[174:177], v[194:197], v[40:43]
	v_mfma_f32_16x16x32_bf16 v[28:31], v[154:157], v[224:227], v[28:31]
	v_mfma_f32_16x16x32_bf16 v[24:27], v[174:177], v[224:227], v[24:27]
	v_mfma_f32_16x16x32_bf16 v[60:63], v[170:173], v[190:193], v[60:63]
	v_mfma_f32_16x16x32_bf16 v[56:59], v[182:185], v[190:193], v[56:59]
	v_mfma_f32_16x16x32_bf16 v[44:47], v[170:173], v[198:201], v[44:47]
	v_mfma_f32_16x16x32_bf16 v[40:43], v[182:185], v[198:201], v[40:43]
	v_mfma_f32_16x16x32_bf16 v[28:31], v[170:173], v[228:231], v[28:31]
	v_mfma_f32_16x16x32_bf16 v[24:27], v[182:185], v[228:231], v[24:27]
	v_mfma_f32_16x16x32_bf16 v[52:55], v[232:235], v[186:189], v[52:55]
	v_mfma_f32_16x16x32_bf16 v[48:51], v[240:243], v[186:189], v[48:51]
	v_mfma_f32_16x16x32_bf16 v[36:39], v[232:235], v[194:197], v[36:39]
	s_add_i32 s71, s71, 2
	v_mfma_f32_16x16x32_bf16 v[32:35], v[240:243], v[194:197], v[32:35]
	s_add_u32 s42, s42, 0x100
	v_mfma_f32_16x16x32_bf16 v[20:23], v[232:235], v[224:227], v[20:23]
	s_addc_u32 s43, s43, 0
	v_mfma_f32_16x16x32_bf16 v[16:19], v[240:243], v[224:227], v[16:19]
	s_add_u32 s69, s69, 0x100
	v_mfma_f32_16x16x32_bf16 v[52:55], v[236:239], v[190:193], v[52:55]
	s_addc_u32 s70, s70, 0
	v_mfma_f32_16x16x32_bf16 v[48:51], v[244:247], v[190:193], v[48:51]
	s_cmp_gt_u32 s71, 13
	v_mfma_f32_16x16x32_bf16 v[36:39], v[236:239], v[198:201], v[36:39]
	v_mfma_f32_16x16x32_bf16 v[32:35], v[244:247], v[198:201], v[32:35]
	v_mfma_f32_16x16x32_bf16 v[20:23], v[236:239], v[228:231], v[20:23]
	v_mfma_f32_16x16x32_bf16 v[16:19], v[244:247], v[228:231], v[16:19]
	s_barrier
	s_setprio 0
	s_cbranch_scc0 .LBB0_465
	s_mul_i32 s42, s67, 0xc0
	s_add_i32 s42, s42, s19
	s_cmpk_lt_u32 s42, 0x2000
	s_cselect_b32 s43, 1, 2
	v_or_b32_e32 v156, s42, v159
	v_mov_b32_e32 v96, s43
	v_cmp_lt_i32_e32 vcc, s23, v156
	v_add_u32_e32 v160, 16, v156
	v_lshl_or_b32 v154, s56, 8, v166
	v_cndmask_b32_e32 v169, 0, v96, vcc
	s_waitcnt vmcnt(0)
	v_add_f32_e32 v96, v126, v127
	v_add_f32_e32 v126, v128, v129
	v_add_f32_e32 v96, v96, v126
	v_mov_b32_e32 v126, v96
	s_nop 1
	v_permlane16_swap_b32_e32 v96, v126
	v_add_f32_e32 v96, v96, v126
	v_mov_b32_e32 v126, v96
	s_nop 1
	v_permlane32_swap_b32_e32 v96, v126
	v_add_f32_e32 v96, v96, v126
	v_fmamk_f32 v96, v96, 0x3a800000, v207
	v_rsq_f32_e32 v162, v96
	v_add_f32_e32 v96, v122, v123
	v_add_f32_e32 v122, v124, v125
	v_add_f32_e32 v96, v96, v122
	v_mov_b32_e32 v122, v96
	s_nop 1
	v_permlane16_swap_b32_e32 v96, v122
	v_add_f32_e32 v96, v96, v122
	v_mov_b32_e32 v122, v96
	s_nop 1
	v_permlane32_swap_b32_e32 v96, v122
	v_add_f32_e32 v96, v96, v122
	v_fmamk_f32 v96, v96, 0x3a800000, v207
	v_rsq_f32_e32 v158, v96
	v_add_f32_e32 v96, v118, v119
	v_add_f32_e32 v118, v120, v121
	v_add_f32_e32 v96, v96, v118
	v_mov_b32_e32 v118, v96
	s_nop 1
	v_permlane16_swap_b32_e32 v96, v118
	v_add_f32_e32 v96, v96, v118
	v_mov_b32_e32 v118, v96
	s_nop 1
	v_permlane32_swap_b32_e32 v96, v118
	v_add_f32_e32 v96, v96, v118
	v_fmamk_f32 v96, v96, 0x3a800000, v207
	v_rsq_f32_e32 v128, v96
	v_add_f32_e32 v96, v114, v115
	v_add_f32_e32 v114, v116, v117
	v_add_f32_e32 v96, v96, v114
	v_mov_b32_e32 v114, v96
	s_nop 1
	v_permlane16_swap_b32_e32 v96, v114
	v_add_f32_e32 v96, v96, v114
	v_mov_b32_e32 v114, v96
	s_nop 1
	v_permlane32_swap_b32_e32 v96, v114
	v_add_f32_e32 v96, v96, v114
	v_fmamk_f32 v96, v96, 0x3a800000, v207
	v_rsq_f32_e32 v126, v96
	v_add_f32_e32 v96, v106, v107
	v_add_f32_e32 v106, v108, v109
	v_add_f32_e32 v96, v96, v106
	v_mov_b32_e32 v106, v96
	s_nop 1
	v_permlane16_swap_b32_e32 v96, v106
	v_add_f32_e32 v96, v96, v106
	v_mov_b32_e32 v106, v96
	s_nop 1
	v_permlane32_swap_b32_e32 v96, v106
	v_add_f32_e32 v96, v96, v106
	v_fmamk_f32 v96, v96, 0x3a800000, v207
	v_rsq_f32_e32 v124, v96
	v_add_f32_e32 v96, v102, v103
	v_add_f32_e32 v102, v104, v105
	v_add_f32_e32 v96, v96, v102
	v_mov_b32_e32 v102, v96
	s_nop 1
	v_permlane16_swap_b32_e32 v96, v102
	v_add_f32_e32 v96, v96, v102
	v_mov_b32_e32 v102, v96
	s_nop 1
	v_permlane32_swap_b32_e32 v96, v102
	v_add_f32_e32 v96, v96, v102
	v_fmamk_f32 v96, v96, 0x3a800000, v207
	v_rsq_f32_e32 v122, v96
	s_mov_b64 s[58:59], -1
	s_cmp_gt_i32 s56, 3
	v_ashrrev_i32_e32 v157, 31, v156
	v_cmp_lt_i32_e32 vcc, s26, v156
	v_cmp_gt_u32_e64 s[42:43], s24, v160
	s_cbranch_scc0 .LBB0_478
	v_lshlrev_b64 v[102:103], 11, v[156:157]
	v_lshl_add_u32 v96, s56, 7, v167
	v_lshl_add_u64 v[102:103], s[48:49], 0, v[102:103]
	v_lshl_add_u64 v[106:107], v[96:97], 1, v[102:103]
	v_pk_fma_f32 v[102:103], v[136:137], v[162:163], v[6:7] op_sel_hi:[1,0,1]
	v_pk_fma_f32 v[104:105], v[134:135], v[162:163], v[4:5] op_sel_hi:[1,0,1]
	v_pk_fma_f32 v[108:109], v[112:113], v[162:163], v[14:15] op_sel_hi:[1,0,1]
	v_pk_fma_f32 v[114:115], v[110:111], v[162:163], v[12:13] op_sel_hi:[1,0,1]
	v_pk_mul_f32 v[108:109], v[102:103], v[108:109]
	v_pk_mul_f32 v[102:103], v[104:105], v[114:115]
	v_pk_fma_f32 v[104:105], v[132:133], v[162:163], v[2:3] op_sel_hi:[1,0,1]
	v_pk_fma_f32 v[114:115], v[130:131], v[162:163], v[0:1] op_sel_hi:[1,0,1]
	v_pk_fma_f32 v[116:117], v[100:101], v[162:163], v[10:11] op_sel_hi:[1,0,1]
	v_pk_fma_f32 v[118:119], v[98:99], v[162:163], v[8:9] op_sel_hi:[1,0,1]
	v_pk_mul_f32 v[116:117], v[104:105], v[116:117]
	v_pk_mul_f32 v[104:105], v[114:115], v[118:119]
	v_cvt_pk_bf16_f32 v102, v102, v103
	v_cvt_pk_bf16_f32 v103, v108, v109
	v_mov_b64_e32 v[120:121], v[14:15]
	v_cvt_pk_bf16_f32 v104, v104, v105
	v_cvt_pk_bf16_f32 v105, v116, v117
	global_store_dwordx4 v[106:107], v[102:105], off
	v_mov_b64_e32 v[116:117], v[10:11]
	v_mov_b64_e32 v[108:109], v[6:7]
	v_cndmask_b32_e64 v102, 2, 1, s[42:43]
	v_cndmask_b32_e32 v125, 0, v102, vcc
	v_mov_b64_e32 v[104:105], v[2:3]
	v_mov_b32_e32 v155, v97
	v_cmp_ne_u32_e32 vcc, v125, v169
	v_mov_b64_e32 v[114:115], v[8:9]
	v_mov_b64_e32 v[102:103], v[0:1]
	v_mov_b64_e32 v[118:119], v[12:13]
	v_mov_b64_e32 v[106:107], v[4:5]
	v_mov_b32_e32 v123, v169
	s_and_saveexec_b64 s[42:43], vcc
	s_cbranch_execz .LBB0_469
	v_mul_u32_u24_e32 v102, 0x7600, v125
	v_lshlrev_b32_e32 v102, 2, v102
	v_mov_b32_e32 v103, v97
	v_lshl_add_u64 v[102:103], s[44:45], 0, v[102:103]
	v_lshl_add_u64 v[118:119], v[154:155], 2, v[102:103]
	global_load_dwordx4 v[102:105], v[118:119], off offset:16
	global_load_dwordx4 v[106:109], v[118:119], off
	global_load_dwordx4 v[114:117], v[118:119], off offset:528
	s_nop 0
	global_load_dwordx4 v[118:121], v[118:119], off offset:512
	v_mov_b32_e32 v123, v125

.LBB0_1020:
	s_add_u32 s44, s84, 0x80
	s_addc_u32 s45, s85, 0
	s_add_u32 s87, s46, 0x100
	s_addc_u32 vcc_lo, s47, 0
	s_mov_b32 s46, 0
	s_waitcnt vmcnt(0)
	s_add_i32 vcc_hi, s46, 2
	s_add_u32 s84, s44, 0x80
	s_addc_u32 s47, s45, 0
	s_add_i32 s29, 0, 0x10000
	v_add_u32_e32 v96, s29, v225
	ds_read_b128 v[56:59], v96
	ds_read_b128 v[68:71], v96 offset:1024
	ds_read_b128 v[80:83], v96 offset:2048
	ds_read_b128 v[98:101], v96 offset:3072
	s_cmp_eq_u32 s90, s46
	s_cselect_b32 s46, s80, s84
	s_cselect_b32 s47, s81, s47
	s_cselect_b32 s85, s83, vcc_lo
	s_cselect_b32 s84, s82, s87
	s_add_i32 m0, s2, 0xc000
	ds_read_b128 v[102:105], v227
	ds_read_b128 v[112:115], v227 offset:1024
	ds_read_b128 v[124:127], v227 offset:2048
	ds_read_b128 v[192:195], v227 offset:3072
	ds_read_b128 v[196:199], v227 offset:4096
	ds_read_b128 v[200:203], v227 offset:5120
	global_load_lds_dwordx4 v188, s[44:45]
	s_add_i32 m0, s2, 0xe000
	s_mov_b64 exec, s[98:99]
	global_load_lds_dwordx4 v190, s[44:45]
	s_mov_b64 exec, -1
	s_add_i32 s96, 0, 0x14000
	s_add_i32 s29, s29, s18
	v_add_u32_e32 v96, s96, v225
	v_lshl_add_u64 v[106:107], s[84:85], 0, v[182:183]
	ds_read_b128 v[228:231], v96
	ds_read_b128 v[232:235], v96 offset:1024
	ds_read_b128 v[236:239], v96 offset:2048
	ds_read_b128 v[240:243], v96 offset:3072
	v_lshl_add_u64 v[248:249], s[84:85], 0, v[186:187]
	s_waitcnt vmcnt(8)
	s_waitcnt lgkmcnt(4)
	s_setprio 1
	s_barrier
	s_waitcnt lgkmcnt(0)
	v_mfma_f32_16x16x32_bf16 v[172:175], v[56:59], v[102:105], 0
	v_mfma_f32_16x16x32_bf16 v[168:171], v[80:83], v[102:105], 0
	v_mfma_f32_16x16x32_bf16 v[156:159], v[56:59], v[124:127], 0
	v_mfma_f32_16x16x32_bf16 v[152:155], v[80:83], v[124:127], 0
	v_mfma_f32_16x16x32_bf16 v[132:135], v[56:59], v[196:199], 0
	v_mfma_f32_16x16x32_bf16 v[128:131], v[80:83], v[196:199], 0
	v_mfma_f32_16x16x32_bf16 v[172:175], v[68:71], v[112:115], v[172:175]
	v_mfma_f32_16x16x32_bf16 v[168:171], v[98:101], v[112:115], v[168:171]
	v_mfma_f32_16x16x32_bf16 v[156:159], v[68:71], v[192:195], v[156:159]
	v_mfma_f32_16x16x32_bf16 v[152:155], v[98:101], v[192:195], v[152:155]
	v_mfma_f32_16x16x32_bf16 v[132:135], v[68:71], v[200:203], v[132:135]
	v_mfma_f32_16x16x32_bf16 v[128:131], v[98:101], v[200:203], v[128:131]
	v_mfma_f32_16x16x32_bf16 v[164:167], v[228:231], v[102:105], 0
	v_mfma_f32_16x16x32_bf16 v[102:105], v[236:239], v[102:105], 0
	v_mfma_f32_16x16x32_bf16 v[120:123], v[228:231], v[196:199], 0
	s_mov_b32 m0, s2
	v_mfma_f32_16x16x32_bf16 v[116:119], v[236:239], v[196:199], 0
	v_lshl_add_u64 v[250:251], s[46:47], 0, v[176:177]
	v_mfma_f32_16x16x32_bf16 v[164:167], v[232:235], v[112:115], v[164:167]
	v_mfma_f32_16x16x32_bf16 v[102:105], v[240:243], v[112:115], v[102:105]
	v_mfma_f32_16x16x32_bf16 v[112:115], v[228:231], v[124:127], 0
	v_mfma_f32_16x16x32_bf16 v[124:127], v[236:239], v[124:127], 0
	v_mfma_f32_16x16x32_bf16 v[120:123], v[232:235], v[200:203], v[120:123]
	v_mfma_f32_16x16x32_bf16 v[116:119], v[240:243], v[200:203], v[116:119]
	v_mfma_f32_16x16x32_bf16 v[112:115], v[232:235], v[192:195], v[112:115]
	v_mfma_f32_16x16x32_bf16 v[124:127], v[240:243], v[192:195], v[124:127]
	s_barrier
	s_setprio 0
	s_mov_b32 m0, s29
	s_nop 0
	global_load_lds_dwordx4 v182, s[84:85]
	s_add_i32 m0, s29, 0x2000
	s_nop 0
	global_load_lds_dwordx4 v186, s[84:85]
	s_mov_b32 m0, s2
	ds_read_b128 v[144:147], v227 offset:16384
	ds_read_b128 v[148:151], v227 offset:17408
	ds_read_b128 v[160:163], v227 offset:18432
	ds_read_b128 v[192:195], v227 offset:19456
	ds_read_b128 v[196:199], v227 offset:20480
	ds_read_b128 v[200:203], v227 offset:21504
	global_load_lds_dwordx4 v176, s[46:47]
	v_lshl_add_u64 v[252:253], s[46:47], 0, v[184:185]
	s_mov_b32 m0, s3
	s_mov_b64 exec, s[98:99]
	global_load_lds_dwordx4 v184, s[46:47]
	s_mov_b64 exec, -1
	s_add_u32 s84, s84, s57
	s_addc_u32 s85, s85, 0
	s_add_i32 s29, s96, s18
	v_lshl_add_u64 v[218:219], s[84:85], 0, v[182:183]
	s_mov_b32 m0, s29
	v_lshl_add_u64 v[220:221], s[84:85], 0, v[186:187]
	global_load_lds_dwordx4 v182, s[84:85]
	s_add_i32 m0, s29, 0x2000
	s_nop 0
	global_load_lds_dwordx4 v186, s[84:85]
	s_waitcnt vmcnt(8)
	s_waitcnt lgkmcnt(0)
	s_setprio 1
	s_barrier
	v_mfma_f32_16x16x32_bf16 v[88:91], v[56:59], v[144:147], 0
	v_mfma_f32_16x16x32_bf16 v[84:87], v[80:83], v[144:147], 0
	v_mfma_f32_16x16x32_bf16 v[52:55], v[56:59], v[160:163], 0
	v_mfma_f32_16x16x32_bf16 v[48:51], v[80:83], v[160:163], 0
	v_mfma_f32_16x16x32_bf16 v[28:31], v[56:59], v[196:199], 0
	v_mfma_f32_16x16x32_bf16 v[24:27], v[80:83], v[196:199], 0
	v_mfma_f32_16x16x32_bf16 v[88:91], v[68:71], v[148:151], v[88:91]
	v_mfma_f32_16x16x32_bf16 v[84:87], v[98:101], v[148:151], v[84:87]
	v_mfma_f32_16x16x32_bf16 v[52:55], v[68:71], v[192:195], v[52:55]
	v_mfma_f32_16x16x32_bf16 v[48:51], v[98:101], v[192:195], v[48:51]
	v_mfma_f32_16x16x32_bf16 v[28:31], v[68:71], v[200:203], v[28:31]
	v_mfma_f32_16x16x32_bf16 v[24:27], v[98:101], v[200:203], v[24:27]
	v_mfma_f32_16x16x32_bf16 v[44:47], v[228:231], v[160:163], 0
	v_mfma_f32_16x16x32_bf16 v[40:43], v[236:239], v[160:163], 0
	v_mfma_f32_16x16x32_bf16 v[20:23], v[228:231], v[196:199], 0
	s_add_i32 s29, 0, 0x18000
	v_mfma_f32_16x16x32_bf16 v[16:19], v[236:239], v[196:199], 0
	v_add_u32_e32 v96, s29, v225
	v_mfma_f32_16x16x32_bf16 v[56:59], v[228:231], v[144:147], 0
	v_mfma_f32_16x16x32_bf16 v[68:71], v[236:239], v[144:147], 0
	v_mfma_f32_16x16x32_bf16 v[44:47], v[232:235], v[192:195], v[44:47]
	v_mfma_f32_16x16x32_bf16 v[40:43], v[240:243], v[192:195], v[40:43]
	v_mfma_f32_16x16x32_bf16 v[20:23], v[232:235], v[200:203], v[20:23]
	v_mfma_f32_16x16x32_bf16 v[16:19], v[240:243], v[200:203], v[16:19]
	v_mfma_f32_16x16x32_bf16 v[56:59], v[232:235], v[148:151], v[56:59]
	v_mfma_f32_16x16x32_bf16 v[68:71], v[240:243], v[148:151], v[68:71]
	s_barrier
	s_setprio 0
	ds_read_b128 v[72:75], v96
	ds_read_b128 v[76:79], v96 offset:1024
	ds_read_b128 v[80:83], v96 offset:2048
	ds_read_b128 v[98:101], v96 offset:3072
	s_add_u32 s46, s46, s64
	s_addc_u32 s47, s47, 0
	s_mov_b32 m0, s4
	ds_read_b128 v[144:147], v227 offset:32768
	ds_read_b128 v[148:151], v227 offset:33792
	ds_read_b128 v[192:195], v227 offset:34816
	ds_read_b128 v[196:199], v227 offset:35840
	ds_read_b128 v[200:203], v227 offset:36864
	ds_read_b128 v[228:231], v227 offset:37888
	global_load_lds_dwordx4 v176, s[46:47]
	s_mov_b32 m0, s5
	s_mov_b64 exec, s[98:99]
	global_load_lds_dwordx4 v184, s[46:47]
	s_mov_b64 exec, -1
	s_add_i32 s46, 0, 0x1c000
	s_add_i32 s29, s29, s18
	v_add_u32_e32 v96, s46, v225
	ds_read_b128 v[232:235], v96
	ds_read_b128 v[236:239], v96 offset:1024
	ds_read_b128 v[240:243], v96 offset:2048
	ds_read_b128 v[244:247], v96 offset:3072
	s_waitcnt vmcnt(8)
	s_waitcnt lgkmcnt(4)
	s_setprio 1
	s_barrier
	s_waitcnt lgkmcnt(0)
	v_mfma_f32_16x16x32_bf16 v[160:163], v[72:75], v[144:147], v[172:175]
	v_mfma_f32_16x16x32_bf16 v[172:175], v[76:79], v[148:151], v[160:163]
	v_mfma_f32_16x16x32_bf16 v[160:163], v[80:83], v[144:147], v[168:171]
	v_mfma_f32_16x16x32_bf16 v[156:159], v[72:75], v[192:195], v[156:159]
	v_mfma_f32_16x16x32_bf16 v[152:155], v[80:83], v[192:195], v[152:155]
	v_mfma_f32_16x16x32_bf16 v[132:135], v[72:75], v[200:203], v[132:135]
	v_mfma_f32_16x16x32_bf16 v[128:131], v[80:83], v[200:203], v[128:131]
	v_mfma_f32_16x16x32_bf16 v[168:171], v[98:101], v[148:151], v[160:163]
	v_mfma_f32_16x16x32_bf16 v[156:159], v[76:79], v[196:199], v[156:159]
	v_mfma_f32_16x16x32_bf16 v[152:155], v[98:101], v[196:199], v[152:155]
	v_mfma_f32_16x16x32_bf16 v[132:135], v[76:79], v[228:231], v[132:135]
	v_mfma_f32_16x16x32_bf16 v[128:131], v[98:101], v[228:231], v[128:131]
	v_mfma_f32_16x16x32_bf16 v[160:163], v[232:235], v[144:147], v[164:167]
	v_mfma_f32_16x16x32_bf16 v[102:105], v[240:243], v[144:147], v[102:105]
	v_mfma_f32_16x16x32_bf16 v[164:167], v[236:239], v[148:151], v[160:163]
	s_mov_b32 m0, s88
	v_mfma_f32_16x16x32_bf16 v[160:163], v[244:247], v[148:151], v[102:105]
	v_lshl_add_u64 v[106:107], v[250:251], 0, s[6:7]
	v_mfma_f32_16x16x32_bf16 v[102:105], v[232:235], v[192:195], v[112:115]
	v_mfma_f32_16x16x32_bf16 v[148:151], v[236:239], v[196:199], v[102:105]
	v_mfma_f32_16x16x32_bf16 v[102:105], v[240:243], v[192:195], v[124:127]
	v_mfma_f32_16x16x32_bf16 v[144:147], v[244:247], v[196:199], v[102:105]
	v_mfma_f32_16x16x32_bf16 v[102:105], v[232:235], v[200:203], v[120:123]
	v_mfma_f32_16x16x32_bf16 v[120:123], v[236:239], v[228:231], v[102:105]
	v_mfma_f32_16x16x32_bf16 v[102:105], v[240:243], v[200:203], v[116:119]
	v_mfma_f32_16x16x32_bf16 v[116:119], v[244:247], v[228:231], v[102:105]
	s_barrier
	s_setprio 0
	s_sub_u32 s100, s6, s57
	s_subb_u32 s101, s7, 0
	v_lshl_add_u64 v[106:107], v[218:219], 0, s[100:101]
	s_mov_b32 m0, s29
	s_nop 0
	global_load_lds_dwordx4 v[106:107], off
	v_lshl_add_u64 v[106:107], v[248:249], 0, s[6:7]
	s_add_i32 m0, s29, 0x2000
	s_nop 0
	global_load_lds_dwordx4 v[106:107], off
	s_mov_b32 m0, s88
	v_lshl_add_u64 v[106:107], v[250:251], 0, s[6:7]
	s_nop 2
	ds_read_b128 v[102:105], v227 offset:49152
	ds_read_b128 v[112:115], v227 offset:50176
	ds_read_b128 v[124:127], v227 offset:51200
	ds_read_b128 v[192:195], v227 offset:52224
	ds_read_b128 v[196:199], v227 offset:53248
	ds_read_b128 v[200:203], v227 offset:54272
	global_load_lds_dwordx4 v[106:107], off
	v_lshl_add_u64 v[106:107], v[252:253], 0, s[6:7]
	s_mov_b32 m0, s89
	s_mov_b64 exec, s[98:99]
	global_load_lds_dwordx4 v[106:107], off
	s_mov_b64 exec, -1
	s_add_i32 s29, s46, s18
	v_lshl_add_u64 v[106:107], v[218:219], 0, s[6:7]
	s_mov_b32 m0, s29
	s_nop 0
	global_load_lds_dwordx4 v[106:107], off
	v_lshl_add_u64 v[106:107], v[220:221], 0, s[6:7]
	s_add_i32 m0, s29, 0x2000
	s_nop 0
	global_load_lds_dwordx4 v[106:107], off
	s_waitcnt vmcnt(8)
	s_waitcnt lgkmcnt(0)
	s_setprio 1
	s_barrier
	v_mfma_f32_16x16x32_bf16 v[88:91], v[72:75], v[102:105], v[88:91]
	v_mfma_f32_16x16x32_bf16 v[84:87], v[80:83], v[102:105], v[84:87]
	v_mfma_f32_16x16x32_bf16 v[52:55], v[72:75], v[124:127], v[52:55]
	v_mfma_f32_16x16x32_bf16 v[48:51], v[80:83], v[124:127], v[48:51]
	v_mfma_f32_16x16x32_bf16 v[28:31], v[72:75], v[196:199], v[28:31]
	v_mfma_f32_16x16x32_bf16 v[24:27], v[80:83], v[196:199], v[24:27]
	v_mfma_f32_16x16x32_bf16 v[88:91], v[76:79], v[112:115], v[88:91]
	v_mfma_f32_16x16x32_bf16 v[84:87], v[98:101], v[112:115], v[84:87]
	v_mfma_f32_16x16x32_bf16 v[52:55], v[76:79], v[192:195], v[52:55]
	v_mfma_f32_16x16x32_bf16 v[48:51], v[98:101], v[192:195], v[48:51]
	v_mfma_f32_16x16x32_bf16 v[28:31], v[76:79], v[200:203], v[28:31]
	v_mfma_f32_16x16x32_bf16 v[24:27], v[98:101], v[200:203], v[24:27]
	v_mfma_f32_16x16x32_bf16 v[56:59], v[232:235], v[102:105], v[56:59]
	v_mfma_f32_16x16x32_bf16 v[76:79], v[236:239], v[112:115], v[56:59]
	v_mfma_f32_16x16x32_bf16 v[56:59], v[240:243], v[102:105], v[68:71]
	s_add_u32 s44, s44, 0x100
	v_mfma_f32_16x16x32_bf16 v[44:47], v[232:235], v[124:127], v[44:47]
	s_addc_u32 s45, s45, 0
	v_mfma_f32_16x16x32_bf16 v[40:43], v[240:243], v[124:127], v[40:43]
	s_add_u32 s87, s87, 0x100
	v_mfma_f32_16x16x32_bf16 v[20:23], v[232:235], v[196:199], v[20:23]
	s_addc_u32 vcc_lo, vcc_lo, 0
	v_mfma_f32_16x16x32_bf16 v[16:19], v[240:243], v[196:199], v[16:19]
	s_cmp_ge_u32 vcc_hi, s37
	v_mfma_f32_16x16x32_bf16 v[72:75], v[244:247], v[112:115], v[56:59]
	s_mov_b32 s46, vcc_hi
	v_mfma_f32_16x16x32_bf16 v[44:47], v[236:239], v[192:195], v[44:47]
	v_mfma_f32_16x16x32_bf16 v[40:43], v[244:247], v[192:195], v[40:43]
	v_mfma_f32_16x16x32_bf16 v[20:23], v[236:239], v[200:203], v[20:23]
	v_mfma_f32_16x16x32_bf16 v[16:19], v[244:247], v[200:203], v[16:19]
	s_barrier
	s_setprio 0
.LBB0_1021:
	s_add_i32 vcc_hi, s46, 2
	s_add_u32 s84, s44, 0x80
	s_addc_u32 s47, s45, 0
	s_add_i32 s29, 0, 0x10000
	v_add_u32_e32 v96, s29, v225
	ds_read_b128 v[56:59], v96
	ds_read_b128 v[68:71], v96 offset:1024
	ds_read_b128 v[80:83], v96 offset:2048
	ds_read_b128 v[98:101], v96 offset:3072
	s_cmp_eq_u32 s90, s46
	s_cselect_b32 s46, s80, s84
	s_cselect_b32 s47, s81, s47
	s_cselect_b32 s85, s83, vcc_lo
	s_cselect_b32 s84, s82, s87
	s_add_i32 m0, s2, 0xc000
	ds_read_b128 v[102:105], v227
	ds_read_b128 v[112:115], v227 offset:1024
	ds_read_b128 v[124:127], v227 offset:2048
	ds_read_b128 v[192:195], v227 offset:3072
	ds_read_b128 v[196:199], v227 offset:4096
	ds_read_b128 v[200:203], v227 offset:5120
	global_load_lds_dwordx4 v188, s[44:45]
	s_add_i32 m0, s2, 0xe000
	s_mov_b64 exec, s[98:99]
	global_load_lds_dwordx4 v190, s[44:45]
	s_mov_b64 exec, -1
	s_add_i32 s96, 0, 0x14000
	s_add_i32 s29, s29, s18
	v_add_u32_e32 v96, s96, v225
	v_lshl_add_u64 v[106:107], s[84:85], 0, v[182:183]
	ds_read_b128 v[228:231], v96
	ds_read_b128 v[232:235], v96 offset:1024
	ds_read_b128 v[236:239], v96 offset:2048
	ds_read_b128 v[240:243], v96 offset:3072
	v_lshl_add_u64 v[248:249], s[84:85], 0, v[186:187]
	s_waitcnt vmcnt(8)
	s_waitcnt lgkmcnt(4)
	s_setprio 1
	s_barrier
	s_waitcnt lgkmcnt(0)
	v_mfma_f32_16x16x32_bf16 v[172:175], v[56:59], v[102:105], v[172:175]
	v_mfma_f32_16x16x32_bf16 v[168:171], v[80:83], v[102:105], v[168:171]
	v_mfma_f32_16x16x32_bf16 v[156:159], v[56:59], v[124:127], v[156:159]
	v_mfma_f32_16x16x32_bf16 v[152:155], v[80:83], v[124:127], v[152:155]
	v_mfma_f32_16x16x32_bf16 v[132:135], v[56:59], v[196:199], v[132:135]
	v_mfma_f32_16x16x32_bf16 v[128:131], v[80:83], v[196:199], v[128:131]
	v_mfma_f32_16x16x32_bf16 v[172:175], v[68:71], v[112:115], v[172:175]
	v_mfma_f32_16x16x32_bf16 v[168:171], v[98:101], v[112:115], v[168:171]
	v_mfma_f32_16x16x32_bf16 v[156:159], v[68:71], v[192:195], v[156:159]
	v_mfma_f32_16x16x32_bf16 v[152:155], v[98:101], v[192:195], v[152:155]
	v_mfma_f32_16x16x32_bf16 v[132:135], v[68:71], v[200:203], v[132:135]
	v_mfma_f32_16x16x32_bf16 v[128:131], v[98:101], v[200:203], v[128:131]
	v_mfma_f32_16x16x32_bf16 v[164:167], v[228:231], v[102:105], v[164:167]
	v_mfma_f32_16x16x32_bf16 v[102:105], v[236:239], v[102:105], v[160:163]
	v_mfma_f32_16x16x32_bf16 v[120:123], v[228:231], v[196:199], v[120:123]
	s_mov_b32 m0, s2
	v_mfma_f32_16x16x32_bf16 v[116:119], v[236:239], v[196:199], v[116:119]
	v_lshl_add_u64 v[250:251], s[46:47], 0, v[176:177]
	v_mfma_f32_16x16x32_bf16 v[164:167], v[232:235], v[112:115], v[164:167]
	v_mfma_f32_16x16x32_bf16 v[102:105], v[240:243], v[112:115], v[102:105]
	v_mfma_f32_16x16x32_bf16 v[112:115], v[228:231], v[124:127], v[148:151]
	v_mfma_f32_16x16x32_bf16 v[124:127], v[236:239], v[124:127], v[144:147]
	v_mfma_f32_16x16x32_bf16 v[120:123], v[232:235], v[200:203], v[120:123]
	v_mfma_f32_16x16x32_bf16 v[116:119], v[240:243], v[200:203], v[116:119]
	v_mfma_f32_16x16x32_bf16 v[112:115], v[232:235], v[192:195], v[112:115]
	v_mfma_f32_16x16x32_bf16 v[124:127], v[240:243], v[192:195], v[124:127]
	s_barrier
	s_setprio 0
	s_mov_b32 m0, s29
	s_nop 0
	global_load_lds_dwordx4 v182, s[84:85]
	s_add_i32 m0, s29, 0x2000
	s_nop 0
	global_load_lds_dwordx4 v186, s[84:85]
	s_mov_b32 m0, s2
	ds_read_b128 v[144:147], v227 offset:16384
	ds_read_b128 v[148:151], v227 offset:17408
	ds_read_b128 v[160:163], v227 offset:18432
	ds_read_b128 v[192:195], v227 offset:19456
	ds_read_b128 v[196:199], v227 offset:20480
	ds_read_b128 v[200:203], v227 offset:21504
	global_load_lds_dwordx4 v176, s[46:47]
	v_lshl_add_u64 v[252:253], s[46:47], 0, v[184:185]
	s_mov_b32 m0, s3
	s_mov_b64 exec, s[98:99]
	global_load_lds_dwordx4 v184, s[46:47]
	s_mov_b64 exec, -1
	s_add_u32 s84, s84, s57
	s_addc_u32 s85, s85, 0
	s_add_i32 s29, s96, s18
	v_lshl_add_u64 v[218:219], s[84:85], 0, v[182:183]
	s_mov_b32 m0, s29
	v_lshl_add_u64 v[220:221], s[84:85], 0, v[186:187]
	global_load_lds_dwordx4 v182, s[84:85]
	s_add_i32 m0, s29, 0x2000
	s_nop 0
	global_load_lds_dwordx4 v186, s[84:85]
	s_waitcnt vmcnt(8)
	s_waitcnt lgkmcnt(0)
	s_setprio 1
	s_barrier
	v_mfma_f32_16x16x32_bf16 v[88:91], v[56:59], v[144:147], v[88:91]
	v_mfma_f32_16x16x32_bf16 v[84:87], v[80:83], v[144:147], v[84:87]
	v_mfma_f32_16x16x32_bf16 v[52:55], v[56:59], v[160:163], v[52:55]
	v_mfma_f32_16x16x32_bf16 v[48:51], v[80:83], v[160:163], v[48:51]
	v_mfma_f32_16x16x32_bf16 v[28:31], v[56:59], v[196:199], v[28:31]
	v_mfma_f32_16x16x32_bf16 v[24:27], v[80:83], v[196:199], v[24:27]
	v_mfma_f32_16x16x32_bf16 v[88:91], v[68:71], v[148:151], v[88:91]
	v_mfma_f32_16x16x32_bf16 v[84:87], v[98:101], v[148:151], v[84:87]
	v_mfma_f32_16x16x32_bf16 v[52:55], v[68:71], v[192:195], v[52:55]
	v_mfma_f32_16x16x32_bf16 v[48:51], v[98:101], v[192:195], v[48:51]
	v_mfma_f32_16x16x32_bf16 v[28:31], v[68:71], v[200:203], v[28:31]
	v_mfma_f32_16x16x32_bf16 v[24:27], v[98:101], v[200:203], v[24:27]
	v_mfma_f32_16x16x32_bf16 v[44:47], v[228:231], v[160:163], v[44:47]
	v_mfma_f32_16x16x32_bf16 v[40:43], v[236:239], v[160:163], v[40:43]
	v_mfma_f32_16x16x32_bf16 v[20:23], v[228:231], v[196:199], v[20:23]
	s_add_i32 s29, 0, 0x18000
	v_mfma_f32_16x16x32_bf16 v[16:19], v[236:239], v[196:199], v[16:19]
	v_add_u32_e32 v96, s29, v225
	v_mfma_f32_16x16x32_bf16 v[56:59], v[228:231], v[144:147], v[76:79]
	v_mfma_f32_16x16x32_bf16 v[68:71], v[236:239], v[144:147], v[72:75]
	v_mfma_f32_16x16x32_bf16 v[44:47], v[232:235], v[192:195], v[44:47]
	v_mfma_f32_16x16x32_bf16 v[40:43], v[240:243], v[192:195], v[40:43]
	v_mfma_f32_16x16x32_bf16 v[20:23], v[232:235], v[200:203], v[20:23]
	v_mfma_f32_16x16x32_bf16 v[16:19], v[240:243], v[200:203], v[16:19]
	v_mfma_f32_16x16x32_bf16 v[56:59], v[232:235], v[148:151], v[56:59]
	v_mfma_f32_16x16x32_bf16 v[68:71], v[240:243], v[148:151], v[68:71]
	s_barrier
	s_setprio 0
	ds_read_b128 v[72:75], v96
	ds_read_b128 v[76:79], v96 offset:1024
	ds_read_b128 v[80:83], v96 offset:2048
	ds_read_b128 v[98:101], v96 offset:3072
	s_add_u32 s46, s46, s64
	s_addc_u32 s47, s47, 0
	s_mov_b32 m0, s4
	ds_read_b128 v[144:147], v227 offset:32768
	ds_read_b128 v[148:151], v227 offset:33792
	ds_read_b128 v[192:195], v227 offset:34816
	ds_read_b128 v[196:199], v227 offset:35840
	ds_read_b128 v[200:203], v227 offset:36864
	ds_read_b128 v[228:231], v227 offset:37888
	global_load_lds_dwordx4 v176, s[46:47]
	s_mov_b32 m0, s5
	s_mov_b64 exec, s[98:99]
	global_load_lds_dwordx4 v184, s[46:47]
	s_mov_b64 exec, -1
	s_add_i32 s46, 0, 0x1c000
	s_add_i32 s29, s29, s18
	v_add_u32_e32 v96, s46, v225
	ds_read_b128 v[232:235], v96
	ds_read_b128 v[236:239], v96 offset:1024
	ds_read_b128 v[240:243], v96 offset:2048
	ds_read_b128 v[244:247], v96 offset:3072
	s_waitcnt vmcnt(8)
	s_waitcnt lgkmcnt(4)
	s_setprio 1
	s_barrier
	s_waitcnt lgkmcnt(0)
	v_mfma_f32_16x16x32_bf16 v[160:163], v[72:75], v[144:147], v[172:175]
	v_mfma_f32_16x16x32_bf16 v[172:175], v[76:79], v[148:151], v[160:163]
	v_mfma_f32_16x16x32_bf16 v[160:163], v[80:83], v[144:147], v[168:171]
	v_mfma_f32_16x16x32_bf16 v[156:159], v[72:75], v[192:195], v[156:159]
	v_mfma_f32_16x16x32_bf16 v[152:155], v[80:83], v[192:195], v[152:155]
	v_mfma_f32_16x16x32_bf16 v[132:135], v[72:75], v[200:203], v[132:135]
	v_mfma_f32_16x16x32_bf16 v[128:131], v[80:83], v[200:203], v[128:131]
	v_mfma_f32_16x16x32_bf16 v[168:171], v[98:101], v[148:151], v[160:163]
	v_mfma_f32_16x16x32_bf16 v[156:159], v[76:79], v[196:199], v[156:159]
	v_mfma_f32_16x16x32_bf16 v[152:155], v[98:101], v[196:199], v[152:155]
	v_mfma_f32_16x16x32_bf16 v[132:135], v[76:79], v[228:231], v[132:135]
	v_mfma_f32_16x16x32_bf16 v[128:131], v[98:101], v[228:231], v[128:131]
	v_mfma_f32_16x16x32_bf16 v[160:163], v[232:235], v[144:147], v[164:167]
	v_mfma_f32_16x16x32_bf16 v[102:105], v[240:243], v[144:147], v[102:105]
	v_mfma_f32_16x16x32_bf16 v[164:167], v[236:239], v[148:151], v[160:163]
	s_mov_b32 m0, s88
	v_mfma_f32_16x16x32_bf16 v[160:163], v[244:247], v[148:151], v[102:105]
	v_lshl_add_u64 v[106:107], v[250:251], 0, s[6:7]
	v_mfma_f32_16x16x32_bf16 v[102:105], v[232:235], v[192:195], v[112:115]
	v_mfma_f32_16x16x32_bf16 v[148:151], v[236:239], v[196:199], v[102:105]
	v_mfma_f32_16x16x32_bf16 v[102:105], v[240:243], v[192:195], v[124:127]
	v_mfma_f32_16x16x32_bf16 v[144:147], v[244:247], v[196:199], v[102:105]
	v_mfma_f32_16x16x32_bf16 v[102:105], v[232:235], v[200:203], v[120:123]
	v_mfma_f32_16x16x32_bf16 v[120:123], v[236:239], v[228:231], v[102:105]
	v_mfma_f32_16x16x32_bf16 v[102:105], v[240:243], v[200:203], v[116:119]
	v_mfma_f32_16x16x32_bf16 v[116:119], v[244:247], v[228:231], v[102:105]
	s_barrier
	s_setprio 0
	s_sub_u32 s100, s6, s57
	s_subb_u32 s101, s7, 0
	v_lshl_add_u64 v[106:107], v[218:219], 0, s[100:101]
	s_mov_b32 m0, s29
	s_nop 0
	global_load_lds_dwordx4 v[106:107], off
	v_lshl_add_u64 v[106:107], v[248:249], 0, s[6:7]
	s_add_i32 m0, s29, 0x2000
	s_nop 0
	global_load_lds_dwordx4 v[106:107], off
	s_mov_b32 m0, s88
	v_lshl_add_u64 v[106:107], v[250:251], 0, s[6:7]
	s_nop 2
	ds_read_b128 v[102:105], v227 offset:49152
	ds_read_b128 v[112:115], v227 offset:50176
	ds_read_b128 v[124:127], v227 offset:51200
	ds_read_b128 v[192:195], v227 offset:52224
	ds_read_b128 v[196:199], v227 offset:53248
	ds_read_b128 v[200:203], v227 offset:54272
	global_load_lds_dwordx4 v[106:107], off
	v_lshl_add_u64 v[106:107], v[252:253], 0, s[6:7]
	s_mov_b32 m0, s89
	s_mov_b64 exec, s[98:99]
	global_load_lds_dwordx4 v[106:107], off
	s_mov_b64 exec, -1
	s_add_i32 s29, s46, s18
	v_lshl_add_u64 v[106:107], v[218:219], 0, s[6:7]
	s_mov_b32 m0, s29
	s_nop 0
	global_load_lds_dwordx4 v[106:107], off
	v_lshl_add_u64 v[106:107], v[220:221], 0, s[6:7]
	s_add_i32 m0, s29, 0x2000
	s_nop 0
	global_load_lds_dwordx4 v[106:107], off
	s_waitcnt vmcnt(8)
	s_waitcnt lgkmcnt(0)
	s_setprio 1
	s_barrier
	v_mfma_f32_16x16x32_bf16 v[88:91], v[72:75], v[102:105], v[88:91]
	v_mfma_f32_16x16x32_bf16 v[84:87], v[80:83], v[102:105], v[84:87]
	v_mfma_f32_16x16x32_bf16 v[52:55], v[72:75], v[124:127], v[52:55]
	v_mfma_f32_16x16x32_bf16 v[48:51], v[80:83], v[124:127], v[48:51]
	v_mfma_f32_16x16x32_bf16 v[28:31], v[72:75], v[196:199], v[28:31]
	v_mfma_f32_16x16x32_bf16 v[24:27], v[80:83], v[196:199], v[24:27]
	v_mfma_f32_16x16x32_bf16 v[88:91], v[76:79], v[112:115], v[88:91]
	v_mfma_f32_16x16x32_bf16 v[84:87], v[98:101], v[112:115], v[84:87]
	v_mfma_f32_16x16x32_bf16 v[52:55], v[76:79], v[192:195], v[52:55]
	v_mfma_f32_16x16x32_bf16 v[48:51], v[98:101], v[192:195], v[48:51]
	v_mfma_f32_16x16x32_bf16 v[28:31], v[76:79], v[200:203], v[28:31]
	v_mfma_f32_16x16x32_bf16 v[24:27], v[98:101], v[200:203], v[24:27]
	v_mfma_f32_16x16x32_bf16 v[56:59], v[232:235], v[102:105], v[56:59]
	v_mfma_f32_16x16x32_bf16 v[76:79], v[236:239], v[112:115], v[56:59]
	v_mfma_f32_16x16x32_bf16 v[56:59], v[240:243], v[102:105], v[68:71]
	s_add_u32 s44, s44, 0x100
	v_mfma_f32_16x16x32_bf16 v[44:47], v[232:235], v[124:127], v[44:47]
	s_addc_u32 s45, s45, 0
	v_mfma_f32_16x16x32_bf16 v[40:43], v[240:243], v[124:127], v[40:43]
	s_add_u32 s87, s87, 0x100
	v_mfma_f32_16x16x32_bf16 v[20:23], v[232:235], v[196:199], v[20:23]
	s_addc_u32 vcc_lo, vcc_lo, 0
	v_mfma_f32_16x16x32_bf16 v[16:19], v[240:243], v[196:199], v[16:19]
	s_cmp_ge_u32 vcc_hi, s37
	v_mfma_f32_16x16x32_bf16 v[72:75], v[244:247], v[112:115], v[56:59]
	s_mov_b32 s46, vcc_hi
	v_mfma_f32_16x16x32_bf16 v[44:47], v[236:239], v[192:195], v[44:47]
	v_mfma_f32_16x16x32_bf16 v[40:43], v[244:247], v[192:195], v[40:43]
	v_mfma_f32_16x16x32_bf16 v[20:23], v[236:239], v[200:203], v[20:23]
	v_mfma_f32_16x16x32_bf16 v[16:19], v[244:247], v[200:203], v[16:19]
	s_barrier
	s_setprio 0
	s_cbranch_scc0 .LBB0_1021
	s_mul_i32 s44, s86, 0xc0
	s_add_i32 s44, s44, s19
	s_cmpk_lt_u32 s44, 0x2000
	v_or_b32_e32 v198, s44, v223
	s_cselect_b32 s44, 1, 2
	v_mov_b32_e32 v56, s44
	v_cmp_lt_i32_e32 vcc, s23, v198
	v_lshl_or_b32 v192, s72, 8, v226
	v_ashrrev_i32_e32 v193, 31, v192
	v_cndmask_b32_e32 v228, 0, v56, vcc
	v_mul_u32_u24_e32 v56, 0x1800, v228
	v_lshlrev_b32_e32 v96, 2, v56
	v_lshl_add_u64 v[56:57], s[70:71], 0, v[96:97]
	v_lshlrev_b64 v[68:69], 2, v[192:193]
	v_lshl_add_u64 v[124:125], v[56:57], 0, v[68:69]
	global_load_dwordx4 v[56:59], v[124:125], off
	v_cndmask_b32_e64 v70, 0, 1, s[78:79]
	v_cmp_ne_u32_e64 s[46:47], 1, v70
	s_andn2_b64 vcc, exec, s[78:79]
	v_lshl_add_u64 v[196:197], s[54:55], 0, v[68:69]
	s_cbranch_vccnz .LBB0_1024
	global_load_dwordx4 v[80:83], v[196:197], off
	s_waitcnt vmcnt(0)
	v_pk_mul_f32 v[58:59], v[58:59], v[82:83]
	v_pk_mul_f32 v[56:57], v[56:57], v[80:81]
